# w_ffn_in transpose items: bias partial sums read sh2 through a per-wave LDS tile (1 load per item) instead of 4 uniform global loads per k-step; S5 unit loads de-serialised
# speedup vs baseline: 1.0164x; 1.0050x over previous
.LBB0_299:
	ds_write2_b32 v191, v128, v129 offset1:1
	ds_write2_b32 v191, v130, v131 offset0:2 offset1:3
	s_waitcnt lgkmcnt(0)
	s_ashr_i32 s35, s34, 31
	s_cmp_eq_u64 s[36:37], 0
	s_cbranch_scc1 .LBB0_303
	s_lshl_b64 s[0:1], s[34:35], 2
	s_add_u32 s0, s6, s0
	v_mov_b32_e32 v130, 0
	s_addc_u32 s1, s7, s1
	v_lshrrev_b32_e32 v216, 4, v132
	v_mul_u32_u24_e32 v216, 0xc000, v216
	v_and_b32_e32 v217, 15, v132
	v_lshl_add_u32 v216, v217, 4, v216
	global_load_dwordx4 v[220:223], v216, s[0:1]
	s_lshl_b32 s13, s24, 10
	s_add_i32 s13, s13, 0x20800
	v_lshl_add_u32 v217, v132, 4, s13
	v_mov_b32_e32 v218, s13
	s_waitcnt vmcnt(0)
	ds_write_b128 v217, v[220:223]
	s_waitcnt lgkmcnt(0)
	s_mov_b32 s13, -4
	v_mov_b32_e32 v136, v155
	v_mov_b32_e32 v131, v130
	v_mov_b32_e32 v128, v130
	v_mov_b32_e32 v129, v130
.LBB0_301:
	ds_read_b128 v[192:195], v218
	ds_read_b128 v[196:199], v218 offset:256
	ds_read_b128 v[200:203], v218 offset:512
	ds_read_b128 v[204:207], v218 offset:768
	ds_read2_b32 v[208:209], v136 offset1:65
	ds_read2_b32 v[210:211], v136 offset0:130 offset1:195
	s_add_i32 s13, s13, 4
	s_add_u32 s0, s0, 16
	s_addc_u32 s1, s1, 0
	v_add_u32_e32 v136, 0x410, v136
	v_add_u32_e32 v218, 16, v218
	s_cmp_gt_u32 s13, 59
	s_waitcnt lgkmcnt(5)
	v_mov_b32_e32 v212, v192
	s_waitcnt lgkmcnt(4)
	v_mov_b32_e32 v213, v196
	s_waitcnt lgkmcnt(1)
	v_pk_fma_f32 v[130:131], v[212:213], v[208:209], v[130:131] op_sel_hi:[1,0,1]
	v_mov_b32_e32 v196, v193
	v_mov_b32_e32 v192, v209
	v_pk_fma_f32 v[130:131], v[196:197], v[192:193], v[130:131] op_sel_hi:[1,0,1]
	v_mov_b32_e32 v196, v194
	v_mov_b32_e32 v197, v198
	s_waitcnt lgkmcnt(0)
	v_pk_fma_f32 v[130:131], v[196:197], v[210:211], v[130:131] op_sel_hi:[1,0,1]
	s_nop 0
	v_mov_b32_e32 v196, v200
	s_nop 0
	v_mov_b32_e32 v197, v204
	v_pk_fma_f32 v[128:129], v[196:197], v[208:209], v[128:129] op_sel_hi:[1,0,1]
	v_mov_b32_e32 v204, v201
	v_pk_fma_f32 v[128:129], v[204:205], v[192:193], v[128:129] op_sel_hi:[1,0,1]
	v_mov_b32_e32 v192, v202
	v_mov_b32_e32 v193, v206
	v_mov_b32_e32 v198, v195
	v_mov_b32_e32 v194, v211
	v_pk_fma_f32 v[128:129], v[192:193], v[210:211], v[128:129] op_sel_hi:[1,0,1]
	v_mov_b32_e32 v206, v203
	v_pk_fma_f32 v[130:131], v[198:199], v[194:195], v[130:131] op_sel_hi:[1,0,1]
	v_pk_fma_f32 v[128:129], v[206:207], v[194:195], v[128:129] op_sel_hi:[1,0,1]
	s_cbranch_scc0 .LBB0_301
	v_lshlrev_b32_e32 v136, 2, v132
	v_lshl_add_u64 v[192:193], s[36:37], 0, v[136:137]
	v_add_co_u32_e32 v194, vcc, 0xb000, v192
	global_atomic_add_f32 v136, v130, s[36:37]
	s_nop 0
	v_addc_co_u32_e32 v195, vcc, 0, v193, vcc
	v_add_co_u32_e32 v130, vcc, 0x16000, v192
	global_atomic_add_f32 v[194:195], v131, off
	s_nop 0
	v_addc_co_u32_e32 v131, vcc, 0, v193, vcc
	global_atomic_add_f32 v[130:131], v128, off
	v_add_co_u32_e32 v130, vcc, 0x21000, v192
	s_nop 1
	v_addc_co_u32_e32 v131, vcc, 0, v193, vcc
	global_atomic_add_f32 v[130:131], v129, off

.LBB0_359:
	ds_write2_b32 v191, v128, v129 offset1:1
	ds_write2_b32 v191, v130, v131 offset0:2 offset1:3
	s_waitcnt lgkmcnt(0)
	s_ashr_i32 s13, s12, 31
	s_cmp_eq_u64 s[48:49], 0
	s_cbranch_scc1 .LBB0_249
	s_lshl_b64 s[0:1], s[12:13], 2
	s_add_u32 s0, s46, s0
	v_mov_b32_e32 v130, 0
	s_addc_u32 s1, s47, s1
	v_lshrrev_b32_e32 v216, 4, v132
	v_mul_u32_u24_e32 v216, 0xc000, v216
	v_and_b32_e32 v217, 15, v132
	v_lshl_add_u32 v216, v217, 4, v216
	global_load_dwordx4 v[220:223], v216, s[0:1]
	s_lshl_b32 s16, s24, 10
	s_add_i32 s16, s16, 0x20800
	v_lshl_add_u32 v217, v132, 4, s16
	v_mov_b32_e32 v218, s16
	s_waitcnt vmcnt(0)
	ds_write_b128 v217, v[220:223]
	s_waitcnt lgkmcnt(0)
	s_mov_b32 s16, -4
	v_mov_b32_e32 v192, v155
	v_mov_b32_e32 v131, v130
	v_mov_b32_e32 v128, v130
	v_mov_b32_e32 v129, v130
.LBB0_361:
	ds_read_b128 v[194:197], v218
	ds_read_b128 v[198:201], v218 offset:256
	ds_read_b128 v[202:205], v218 offset:512
	ds_read_b128 v[206:209], v218 offset:768
	ds_read2_b32 v[210:211], v192 offset1:65
	ds_read2_b32 v[212:213], v192 offset0:130 offset1:195
	s_add_i32 s16, s16, 4
	s_add_u32 s0, s0, 16
	s_addc_u32 s1, s1, 0
	v_add_u32_e32 v192, 0x410, v192
	v_add_u32_e32 v218, 16, v218
	s_cmp_gt_u32 s16, 59
	s_waitcnt lgkmcnt(5)
	v_mov_b32_e32 v214, v194
	s_waitcnt lgkmcnt(4)
	v_mov_b32_e32 v215, v198
	s_waitcnt lgkmcnt(1)
	v_pk_fma_f32 v[130:131], v[214:215], v[210:211], v[130:131] op_sel_hi:[1,0,1]
	v_mov_b32_e32 v198, v195
	v_mov_b32_e32 v194, v211
	v_pk_fma_f32 v[130:131], v[198:199], v[194:195], v[130:131] op_sel_hi:[1,0,1]
	v_mov_b32_e32 v198, v196
	v_mov_b32_e32 v199, v200
	s_waitcnt lgkmcnt(0)
	v_pk_fma_f32 v[130:131], v[198:199], v[212:213], v[130:131] op_sel_hi:[1,0,1]
	s_nop 0
	v_mov_b32_e32 v198, v202
	s_nop 0
	v_mov_b32_e32 v199, v206
	v_pk_fma_f32 v[128:129], v[198:199], v[210:211], v[128:129] op_sel_hi:[1,0,1]
	v_mov_b32_e32 v206, v203
	v_pk_fma_f32 v[128:129], v[206:207], v[194:195], v[128:129] op_sel_hi:[1,0,1]
	v_mov_b32_e32 v194, v204
	v_mov_b32_e32 v195, v208
	v_mov_b32_e32 v200, v197
	v_mov_b32_e32 v196, v213
	v_pk_fma_f32 v[128:129], v[194:195], v[212:213], v[128:129] op_sel_hi:[1,0,1]
	v_mov_b32_e32 v208, v205
	v_pk_fma_f32 v[130:131], v[200:201], v[196:197], v[130:131] op_sel_hi:[1,0,1]
	v_pk_fma_f32 v[128:129], v[208:209], v[196:197], v[128:129] op_sel_hi:[1,0,1]
	s_cbranch_scc0 .LBB0_361
	v_lshlrev_b32_e32 v192, 2, v132
	v_mov_b32_e32 v193, v137
	v_lshl_add_u64 v[194:195], s[48:49], 0, v[192:193]
	global_atomic_add_f32 v192, v130, s[48:49]
	v_add_co_u32_e32 v192, vcc, 0xb000, v194
	s_nop 1
	v_addc_co_u32_e32 v193, vcc, 0, v195, vcc
	v_add_co_u32_e32 v130, vcc, 0x16000, v194
	global_atomic_add_f32 v[192:193], v131, off
	s_nop 0
	v_addc_co_u32_e32 v131, vcc, 0, v195, vcc
	global_atomic_add_f32 v[130:131], v128, off
	v_add_co_u32_e32 v130, vcc, 0x21000, v194
	s_nop 1
	v_addc_co_u32_e32 v131, vcc, 0, v195, vcc
	global_atomic_add_f32 v[130:131], v129, off
	s_branch .LBB0_249

.LBB0_435:
	v_mov_b32_e32 v52, v252
	s_movk_i32 s1, 0x1200
	v_lshlrev_b32_e32 v0, 4, v52
	s_and_b32 s23, s22, 63
	s_ashr_i32 s0, s22, 6
	v_readfirstlane_b32 s24, v52
	v_cmp_gt_i32_e32 vcc, s1, v52
	v_and_b32_e32 v234, 16, v0
	s_and_saveexec_b64 s[4:5], vcc
	s_cbranch_execz .LBB0_442
	s_ashr_i32 s1, s0, 31
	s_lshl_b64 s[6:7], s[0:1], 11
	s_add_u32 s6, s6, 0xffffff00
	s_addc_u32 s7, s7, -1
	s_lshl_b32 s1, s0, 8
	s_ashr_i32 s13, s1, 31
	s_add_u32 s12, s1, 0x2000
	s_addc_u32 s13, s13, 0
	s_lshl_b32 s1, s23, 5
	s_add_u32 s14, s96, s1
	s_addc_u32 s15, s97, 0
	v_mov_b32_e32 v235, v233
	v_lshl_add_u64 v[0:1], s[14:15], 0, v[234:235]
	s_mov_b64 s[14:15], 0
	v_mov_b32_e32 v6, v52
	v_ashrrev_i32_e32 v2, 1, v52
	v_mov_b32_e32 v3, v233
	v_lshl_add_u64 v[4:5], s[12:13], 0, v[2:3]
	v_lshlrev_b64 v[4:5], 11, v[4:5]
	v_lshl_add_u64 v[4:5], v[0:1], 0, v[4:5]
	global_load_dwordx4 v[76:79], v[4:5], off
	s_add_u32 s14, s6, 0x100
	s_addc_u32 s15, s7, 0
	v_lshl_add_u64 v[4:5], s[14:15], 0, v[2:3]
	v_lshlrev_b64 v[4:5], 11, v[4:5]
	v_lshl_add_u64 v[4:5], v[0:1], 0, v[4:5]
	s_mov_b32 s14, 0x80000
	s_mov_b32 s15, 0
	global_load_dwordx4 v[80:83], v[4:5], off
	v_lshl_add_u64 v[4:5], v[4:5], 0, s[14:15]
	global_load_dwordx4 v[84:87], v[4:5], off
	v_lshl_add_u64 v[4:5], v[4:5], 0, s[14:15]
	global_load_dwordx4 v[88:91], v[4:5], off
	v_lshl_add_u64 v[4:5], v[4:5], 0, s[14:15]
	global_load_dwordx4 v[92:95], v[4:5], off
	v_lshl_add_u64 v[4:5], v[4:5], 0, s[14:15]
	global_load_dwordx4 v[96:99], v[4:5], off
	v_lshl_add_u64 v[4:5], v[4:5], 0, s[14:15]
	global_load_dwordx4 v[100:103], v[4:5], off
	v_lshl_add_u64 v[4:5], v[4:5], 0, s[14:15]
	global_load_dwordx4 v[104:107], v[4:5], off
	v_lshl_add_u64 v[4:5], v[4:5], 0, s[14:15]
	global_load_dwordx4 v[108:111], v[4:5], off
	v_lshrrev_b32_e32 v6, 6, v52
	s_movk_i32 s14, 0x410
	v_mul_lo_u32 v6, v6, s14
	v_lshlrev_b32_e32 v7, 4, v52
	v_and_b32_e32 v7, 0x3e0, v7
	v_add3_u32 v6, v6, v7, v234
	v_add_u32_e32 v7, 0x2080, v6
	s_waitcnt vmcnt(8)
	ds_write_b128 v6, v[76:79]
	s_waitcnt vmcnt(7)
	ds_write_b128 v6, v[80:83] offset:8320
	s_waitcnt vmcnt(6)
	ds_write_b128 v6, v[84:87] offset:16640
	s_waitcnt vmcnt(5)
	ds_write_b128 v6, v[88:91] offset:24960
	s_waitcnt vmcnt(4)
	ds_write_b128 v6, v[92:95] offset:33280
	s_waitcnt vmcnt(3)
	ds_write_b128 v6, v[96:99] offset:41600
	s_waitcnt vmcnt(2)
	ds_write_b128 v6, v[100:103] offset:49920
	s_waitcnt vmcnt(1)
	ds_write_b128 v6, v[104:107] offset:58240
	s_waitcnt vmcnt(0)
	ds_write_b128 v7, v[108:111] offset:58240

.LBB0_443:
	s_mov_b32 s7, 0
	s_mov_b32 s6, 0xfc00000
	v_lshl_add_u64 v[50:51], v[48:49], 0, s[6:7]
	global_load_dwordx4 v[76:79], v[50:51], off
	s_mov_b32 s6, 0xfc02000
	v_lshl_add_u64 v[50:51], v[48:49], 0, s[6:7]
	global_load_dwordx4 v[80:83], v[50:51], off
	s_mov_b32 s6, 0xfc04000
	v_lshl_add_u64 v[50:51], v[48:49], 0, s[6:7]
	global_load_dwordx4 v[84:87], v[50:51], off
	s_mov_b32 s6, 0xfc06000
	v_lshl_add_u64 v[50:51], v[48:49], 0, s[6:7]
	global_load_dwordx4 v[88:91], v[50:51], off
	s_mov_b32 s6, 0xfc08000
	v_lshl_add_u64 v[50:51], v[48:49], 0, s[6:7]
	global_load_dwordx4 v[92:95], v[50:51], off
	s_mov_b32 s6, 0xfc0a000
	v_lshl_add_u64 v[50:51], v[48:49], 0, s[6:7]
	global_load_dwordx4 v[96:99], v[50:51], off
	s_mov_b32 s6, 0xfc0c000
	v_lshl_add_u64 v[50:51], v[48:49], 0, s[6:7]
	global_load_dwordx4 v[100:103], v[50:51], off
	s_mov_b32 s6, 0xfc0e000
	v_lshl_add_u64 v[50:51], v[48:49], 0, s[6:7]
	global_load_dwordx4 v[104:107], v[50:51], off
	s_mov_b32 s6, 0xfc10000
	v_lshl_add_u64 v[50:51], v[48:49], 0, s[6:7]
	global_load_dwordx4 v[108:111], v[50:51], off
	s_mov_b32 s6, 0xfc12000
	v_lshl_add_u64 v[50:51], v[48:49], 0, s[6:7]
	global_load_dwordx4 v[112:115], v[50:51], off
	s_mov_b32 s6, 0xfc14000
	v_lshl_add_u64 v[50:51], v[48:49], 0, s[6:7]
	global_load_dwordx4 v[116:119], v[50:51], off
	s_mov_b32 s6, 0xfc16000
	v_lshl_add_u64 v[50:51], v[48:49], 0, s[6:7]
	global_load_dwordx4 v[120:123], v[50:51], off
	s_mov_b32 s6, 0xfc18000
	v_lshl_add_u64 v[50:51], v[48:49], 0, s[6:7]
	global_load_dwordx4 v[124:127], v[50:51], off
	s_mov_b32 s6, 0xfc1a000
	v_lshl_add_u64 v[50:51], v[48:49], 0, s[6:7]
	global_load_dwordx4 v[128:131], v[50:51], off
	s_mov_b32 s6, 0xfc1c000
	v_lshl_add_u64 v[50:51], v[48:49], 0, s[6:7]
	global_load_dwordx4 v[132:135], v[50:51], off
	s_mov_b32 s6, 0xfc1e000
	v_lshl_add_u64 v[50:51], v[48:49], 0, s[6:7]
	global_load_dwordx4 v[136:139], v[50:51], off
	s_mov_b32 s6, 0xfc20000
	v_lshl_add_u64 v[50:51], v[48:49], 0, s[6:7]
	global_load_dwordx4 v[140:143], v[50:51], off
	s_mov_b32 s6, 0xfc22000
	v_lshl_add_u64 v[50:51], v[48:49], 0, s[6:7]
	global_load_dwordx4 v[144:147], v[50:51], off
	s_mov_b32 s6, 0xfc24000
	v_lshl_add_u64 v[50:51], v[48:49], 0, s[6:7]
	global_load_dwordx4 v[148:151], v[50:51], off
	s_mov_b32 s6, 0xfc26000
	v_lshl_add_u64 v[50:51], v[48:49], 0, s[6:7]
	global_load_dwordx4 v[152:155], v[50:51], off
	s_mov_b32 s6, 0xfc28000
	v_lshl_add_u64 v[50:51], v[48:49], 0, s[6:7]
	global_load_dwordx4 v[156:159], v[50:51], off
	s_mov_b32 s6, 0xfc2a000
	v_lshl_add_u64 v[50:51], v[48:49], 0, s[6:7]
	global_load_dwordx4 v[160:163], v[50:51], off
	s_mov_b32 s6, 0xfc2c000
	v_lshl_add_u64 v[50:51], v[48:49], 0, s[6:7]
	global_load_dwordx4 v[164:167], v[50:51], off
	s_mov_b32 s6, 0xfc2e000
	v_lshl_add_u64 v[50:51], v[48:49], 0, s[6:7]
	global_load_dwordx4 v[168:171], v[50:51], off
	s_mov_b32 s6, 0xfc30000
	v_lshl_add_u64 v[50:51], v[48:49], 0, s[6:7]
	global_load_dwordx4 v[172:175], v[50:51], off
	s_mov_b32 s6, 0xfc32000
	v_lshl_add_u64 v[50:51], v[48:49], 0, s[6:7]
	global_load_dwordx4 v[176:179], v[50:51], off
	s_mov_b32 s6, 0xfc34000
	v_lshl_add_u64 v[50:51], v[48:49], 0, s[6:7]
	global_load_dwordx4 v[180:183], v[50:51], off
	s_mov_b32 s6, 0xfc36000
	v_lshl_add_u64 v[50:51], v[48:49], 0, s[6:7]
	global_load_dwordx4 v[184:187], v[50:51], off
	s_mov_b32 s6, 0xfc38000
	v_lshl_add_u64 v[50:51], v[48:49], 0, s[6:7]
	global_load_dwordx4 v[188:191], v[50:51], off
	s_mov_b32 s6, 0xfc3a000
	v_lshl_add_u64 v[50:51], v[48:49], 0, s[6:7]
	global_load_dwordx4 v[192:195], v[50:51], off
	s_mov_b32 s6, 0xfc3c000
	v_lshl_add_u64 v[50:51], v[48:49], 0, s[6:7]
	global_load_dwordx4 v[196:199], v[50:51], off
	s_mov_b32 s6, 0xfc3e000
	v_lshl_add_u64 v[50:51], v[48:49], 0, s[6:7]
	global_load_dwordx4 v[200:203], v[50:51], off
	ds_read_b128 v[204:207], v54 offset:0
	ds_read_b128 v[208:211], v54 offset:33280
	ds_read_b128 v[212:215], v55 offset:0
	ds_read_b128 v[216:219], v54 offset:32
	ds_read_b128 v[220:223], v54 offset:33312
	ds_read_b128 v[224:227], v55 offset:32
	s_waitcnt vmcnt(31) lgkmcnt(3)
	v_mfma_f32_32x32x16_bf16 v[0:15], v[76:79], v[204:207], v[0:15]
	v_mfma_f32_32x32x16_bf16 v[16:31], v[76:79], v[208:211], v[16:31]
	v_mfma_f32_32x32x16_bf16 v[32:47], v[76:79], v[212:215], v[32:47]
	ds_read_b128 v[204:207], v54 offset:64
	ds_read_b128 v[208:211], v54 offset:33344
	ds_read_b128 v[212:215], v55 offset:64
	s_waitcnt vmcnt(30) lgkmcnt(3)
	v_mfma_f32_32x32x16_bf16 v[0:15], v[80:83], v[216:219], v[0:15]
	v_mfma_f32_32x32x16_bf16 v[16:31], v[80:83], v[220:223], v[16:31]
	v_mfma_f32_32x32x16_bf16 v[32:47], v[80:83], v[224:227], v[32:47]
	ds_read_b128 v[216:219], v54 offset:96
	ds_read_b128 v[220:223], v54 offset:33376
	ds_read_b128 v[224:227], v55 offset:96
	s_waitcnt vmcnt(29) lgkmcnt(3)
	v_mfma_f32_32x32x16_bf16 v[0:15], v[84:87], v[204:207], v[0:15]
	v_mfma_f32_32x32x16_bf16 v[16:31], v[84:87], v[208:211], v[16:31]
	v_mfma_f32_32x32x16_bf16 v[32:47], v[84:87], v[212:215], v[32:47]
	ds_read_b128 v[204:207], v54 offset:128
	ds_read_b128 v[208:211], v54 offset:33408
	ds_read_b128 v[212:215], v55 offset:128
	s_waitcnt vmcnt(28) lgkmcnt(3)
	v_mfma_f32_32x32x16_bf16 v[0:15], v[88:91], v[216:219], v[0:15]
	v_mfma_f32_32x32x16_bf16 v[16:31], v[88:91], v[220:223], v[16:31]
	v_mfma_f32_32x32x16_bf16 v[32:47], v[88:91], v[224:227], v[32:47]
	ds_read_b128 v[216:219], v54 offset:160
	ds_read_b128 v[220:223], v54 offset:33440
	ds_read_b128 v[224:227], v55 offset:160
	s_waitcnt vmcnt(27) lgkmcnt(3)
	v_mfma_f32_32x32x16_bf16 v[0:15], v[92:95], v[204:207], v[0:15]
	v_mfma_f32_32x32x16_bf16 v[16:31], v[92:95], v[208:211], v[16:31]
	v_mfma_f32_32x32x16_bf16 v[32:47], v[92:95], v[212:215], v[32:47]
	ds_read_b128 v[204:207], v54 offset:192
	ds_read_b128 v[208:211], v54 offset:33472
	ds_read_b128 v[212:215], v55 offset:192
	s_waitcnt vmcnt(26) lgkmcnt(3)
	v_mfma_f32_32x32x16_bf16 v[0:15], v[96:99], v[216:219], v[0:15]
	v_mfma_f32_32x32x16_bf16 v[16:31], v[96:99], v[220:223], v[16:31]
	v_mfma_f32_32x32x16_bf16 v[32:47], v[96:99], v[224:227], v[32:47]
	ds_read_b128 v[216:219], v54 offset:224
	ds_read_b128 v[220:223], v54 offset:33504
	ds_read_b128 v[224:227], v55 offset:224
	s_waitcnt vmcnt(25) lgkmcnt(3)
	v_mfma_f32_32x32x16_bf16 v[0:15], v[100:103], v[204:207], v[0:15]
	v_mfma_f32_32x32x16_bf16 v[16:31], v[100:103], v[208:211], v[16:31]
	v_mfma_f32_32x32x16_bf16 v[32:47], v[100:103], v[212:215], v[32:47]
	ds_read_b128 v[204:207], v54 offset:256
	ds_read_b128 v[208:211], v54 offset:33536
	ds_read_b128 v[212:215], v55 offset:256
	s_waitcnt vmcnt(24) lgkmcnt(3)
	v_mfma_f32_32x32x16_bf16 v[0:15], v[104:107], v[216:219], v[0:15]
	v_mfma_f32_32x32x16_bf16 v[16:31], v[104:107], v[220:223], v[16:31]
	v_mfma_f32_32x32x16_bf16 v[32:47], v[104:107], v[224:227], v[32:47]
	ds_read_b128 v[216:219], v54 offset:288
	ds_read_b128 v[220:223], v54 offset:33568
	ds_read_b128 v[224:227], v55 offset:288
	s_waitcnt vmcnt(23) lgkmcnt(3)
	v_mfma_f32_32x32x16_bf16 v[0:15], v[108:111], v[204:207], v[0:15]
	v_mfma_f32_32x32x16_bf16 v[16:31], v[108:111], v[208:211], v[16:31]
	v_mfma_f32_32x32x16_bf16 v[32:47], v[108:111], v[212:215], v[32:47]
	ds_read_b128 v[204:207], v54 offset:320
	ds_read_b128 v[208:211], v54 offset:33600
	ds_read_b128 v[212:215], v55 offset:320
	s_waitcnt vmcnt(22) lgkmcnt(3)
	v_mfma_f32_32x32x16_bf16 v[0:15], v[112:115], v[216:219], v[0:15]
	v_mfma_f32_32x32x16_bf16 v[16:31], v[112:115], v[220:223], v[16:31]
	v_mfma_f32_32x32x16_bf16 v[32:47], v[112:115], v[224:227], v[32:47]
	ds_read_b128 v[216:219], v54 offset:352
	ds_read_b128 v[220:223], v54 offset:33632
	ds_read_b128 v[224:227], v55 offset:352
	s_waitcnt vmcnt(21) lgkmcnt(3)
	v_mfma_f32_32x32x16_bf16 v[0:15], v[116:119], v[204:207], v[0:15]
	v_mfma_f32_32x32x16_bf16 v[16:31], v[116:119], v[208:211], v[16:31]
	v_mfma_f32_32x32x16_bf16 v[32:47], v[116:119], v[212:215], v[32:47]
	ds_read_b128 v[204:207], v54 offset:384
	ds_read_b128 v[208:211], v54 offset:33664
	ds_read_b128 v[212:215], v55 offset:384
	s_waitcnt vmcnt(20) lgkmcnt(3)
	v_mfma_f32_32x32x16_bf16 v[0:15], v[120:123], v[216:219], v[0:15]
	v_mfma_f32_32x32x16_bf16 v[16:31], v[120:123], v[220:223], v[16:31]
	v_mfma_f32_32x32x16_bf16 v[32:47], v[120:123], v[224:227], v[32:47]
	ds_read_b128 v[216:219], v54 offset:416
	ds_read_b128 v[220:223], v54 offset:33696
	ds_read_b128 v[224:227], v55 offset:416
	s_waitcnt vmcnt(19) lgkmcnt(3)
	v_mfma_f32_32x32x16_bf16 v[0:15], v[124:127], v[204:207], v[0:15]
	v_mfma_f32_32x32x16_bf16 v[16:31], v[124:127], v[208:211], v[16:31]
	v_mfma_f32_32x32x16_bf16 v[32:47], v[124:127], v[212:215], v[32:47]
	ds_read_b128 v[204:207], v54 offset:448
	ds_read_b128 v[208:211], v54 offset:33728
	ds_read_b128 v[212:215], v55 offset:448
	s_waitcnt vmcnt(18) lgkmcnt(3)
	v_mfma_f32_32x32x16_bf16 v[0:15], v[128:131], v[216:219], v[0:15]
	v_mfma_f32_32x32x16_bf16 v[16:31], v[128:131], v[220:223], v[16:31]
	v_mfma_f32_32x32x16_bf16 v[32:47], v[128:131], v[224:227], v[32:47]
	ds_read_b128 v[216:219], v54 offset:480
	ds_read_b128 v[220:223], v54 offset:33760
	ds_read_b128 v[224:227], v55 offset:480
	s_waitcnt vmcnt(17) lgkmcnt(3)
	v_mfma_f32_32x32x16_bf16 v[0:15], v[132:135], v[204:207], v[0:15]
	v_mfma_f32_32x32x16_bf16 v[16:31], v[132:135], v[208:211], v[16:31]
	v_mfma_f32_32x32x16_bf16 v[32:47], v[132:135], v[212:215], v[32:47]
	ds_read_b128 v[204:207], v54 offset:512
	ds_read_b128 v[208:211], v54 offset:33792
	ds_read_b128 v[212:215], v55 offset:512
	s_waitcnt vmcnt(16) lgkmcnt(3)
	v_mfma_f32_32x32x16_bf16 v[0:15], v[136:139], v[216:219], v[0:15]
	v_mfma_f32_32x32x16_bf16 v[16:31], v[136:139], v[220:223], v[16:31]
	v_mfma_f32_32x32x16_bf16 v[32:47], v[136:139], v[224:227], v[32:47]
	ds_read_b128 v[216:219], v54 offset:544
	ds_read_b128 v[220:223], v54 offset:33824
	ds_read_b128 v[224:227], v55 offset:544
	s_waitcnt vmcnt(15) lgkmcnt(3)
	v_mfma_f32_32x32x16_bf16 v[0:15], v[140:143], v[204:207], v[0:15]
	v_mfma_f32_32x32x16_bf16 v[16:31], v[140:143], v[208:211], v[16:31]
	v_mfma_f32_32x32x16_bf16 v[32:47], v[140:143], v[212:215], v[32:47]
	ds_read_b128 v[204:207], v54 offset:576
	ds_read_b128 v[208:211], v54 offset:33856
	ds_read_b128 v[212:215], v55 offset:576
	s_waitcnt vmcnt(14) lgkmcnt(3)
	v_mfma_f32_32x32x16_bf16 v[0:15], v[144:147], v[216:219], v[0:15]
	v_mfma_f32_32x32x16_bf16 v[16:31], v[144:147], v[220:223], v[16:31]
	v_mfma_f32_32x32x16_bf16 v[32:47], v[144:147], v[224:227], v[32:47]
	ds_read_b128 v[216:219], v54 offset:608
	ds_read_b128 v[220:223], v54 offset:33888
	ds_read_b128 v[224:227], v55 offset:608
	s_waitcnt vmcnt(13) lgkmcnt(3)
	v_mfma_f32_32x32x16_bf16 v[0:15], v[148:151], v[204:207], v[0:15]
	v_mfma_f32_32x32x16_bf16 v[16:31], v[148:151], v[208:211], v[16:31]
	v_mfma_f32_32x32x16_bf16 v[32:47], v[148:151], v[212:215], v[32:47]
	ds_read_b128 v[204:207], v54 offset:640
	ds_read_b128 v[208:211], v54 offset:33920
	ds_read_b128 v[212:215], v55 offset:640
	s_waitcnt vmcnt(12) lgkmcnt(3)
	v_mfma_f32_32x32x16_bf16 v[0:15], v[152:155], v[216:219], v[0:15]
	v_mfma_f32_32x32x16_bf16 v[16:31], v[152:155], v[220:223], v[16:31]
	v_mfma_f32_32x32x16_bf16 v[32:47], v[152:155], v[224:227], v[32:47]
	ds_read_b128 v[216:219], v54 offset:672
	ds_read_b128 v[220:223], v54 offset:33952
	ds_read_b128 v[224:227], v55 offset:672
	s_waitcnt vmcnt(11) lgkmcnt(3)
	v_mfma_f32_32x32x16_bf16 v[0:15], v[156:159], v[204:207], v[0:15]
	v_mfma_f32_32x32x16_bf16 v[16:31], v[156:159], v[208:211], v[16:31]
	v_mfma_f32_32x32x16_bf16 v[32:47], v[156:159], v[212:215], v[32:47]
	ds_read_b128 v[204:207], v54 offset:704
	ds_read_b128 v[208:211], v54 offset:33984
	ds_read_b128 v[212:215], v55 offset:704
	s_waitcnt vmcnt(10) lgkmcnt(3)
	v_mfma_f32_32x32x16_bf16 v[0:15], v[160:163], v[216:219], v[0:15]
	v_mfma_f32_32x32x16_bf16 v[16:31], v[160:163], v[220:223], v[16:31]
	v_mfma_f32_32x32x16_bf16 v[32:47], v[160:163], v[224:227], v[32:47]
	ds_read_b128 v[216:219], v54 offset:736
	ds_read_b128 v[220:223], v54 offset:34016
	ds_read_b128 v[224:227], v55 offset:736
	s_waitcnt vmcnt(9) lgkmcnt(3)
	v_mfma_f32_32x32x16_bf16 v[0:15], v[164:167], v[204:207], v[0:15]
	v_mfma_f32_32x32x16_bf16 v[16:31], v[164:167], v[208:211], v[16:31]
	v_mfma_f32_32x32x16_bf16 v[32:47], v[164:167], v[212:215], v[32:47]
	ds_read_b128 v[204:207], v54 offset:768
	ds_read_b128 v[208:211], v54 offset:34048
	ds_read_b128 v[212:215], v55 offset:768
	s_waitcnt vmcnt(8) lgkmcnt(3)
	v_mfma_f32_32x32x16_bf16 v[0:15], v[168:171], v[216:219], v[0:15]
	v_mfma_f32_32x32x16_bf16 v[16:31], v[168:171], v[220:223], v[16:31]
	v_mfma_f32_32x32x16_bf16 v[32:47], v[168:171], v[224:227], v[32:47]
	ds_read_b128 v[216:219], v54 offset:800
	ds_read_b128 v[220:223], v54 offset:34080
	ds_read_b128 v[224:227], v55 offset:800
	s_waitcnt vmcnt(7) lgkmcnt(3)
	v_mfma_f32_32x32x16_bf16 v[0:15], v[172:175], v[204:207], v[0:15]
	v_mfma_f32_32x32x16_bf16 v[16:31], v[172:175], v[208:211], v[16:31]
	v_mfma_f32_32x32x16_bf16 v[32:47], v[172:175], v[212:215], v[32:47]
	ds_read_b128 v[204:207], v54 offset:832
	ds_read_b128 v[208:211], v54 offset:34112
	ds_read_b128 v[212:215], v55 offset:832
	s_waitcnt vmcnt(6) lgkmcnt(3)
	v_mfma_f32_32x32x16_bf16 v[0:15], v[176:179], v[216:219], v[0:15]
	v_mfma_f32_32x32x16_bf16 v[16:31], v[176:179], v[220:223], v[16:31]
	v_mfma_f32_32x32x16_bf16 v[32:47], v[176:179], v[224:227], v[32:47]
	ds_read_b128 v[216:219], v54 offset:864
	ds_read_b128 v[220:223], v54 offset:34144
	ds_read_b128 v[224:227], v55 offset:864
	s_waitcnt vmcnt(5) lgkmcnt(3)
	v_mfma_f32_32x32x16_bf16 v[0:15], v[180:183], v[204:207], v[0:15]
	v_mfma_f32_32x32x16_bf16 v[16:31], v[180:183], v[208:211], v[16:31]
	v_mfma_f32_32x32x16_bf16 v[32:47], v[180:183], v[212:215], v[32:47]
	ds_read_b128 v[204:207], v54 offset:896
	ds_read_b128 v[208:211], v54 offset:34176
	ds_read_b128 v[212:215], v55 offset:896
	s_waitcnt vmcnt(4) lgkmcnt(3)
	v_mfma_f32_32x32x16_bf16 v[0:15], v[184:187], v[216:219], v[0:15]
	v_mfma_f32_32x32x16_bf16 v[16:31], v[184:187], v[220:223], v[16:31]
	v_mfma_f32_32x32x16_bf16 v[32:47], v[184:187], v[224:227], v[32:47]
	ds_read_b128 v[216:219], v54 offset:928
	ds_read_b128 v[220:223], v54 offset:34208
	ds_read_b128 v[224:227], v55 offset:928
	s_waitcnt vmcnt(3) lgkmcnt(3)
	v_mfma_f32_32x32x16_bf16 v[0:15], v[188:191], v[204:207], v[0:15]
	v_mfma_f32_32x32x16_bf16 v[16:31], v[188:191], v[208:211], v[16:31]
	v_mfma_f32_32x32x16_bf16 v[32:47], v[188:191], v[212:215], v[32:47]
	ds_read_b128 v[204:207], v54 offset:960
	ds_read_b128 v[208:211], v54 offset:34240
	ds_read_b128 v[212:215], v55 offset:960
	s_waitcnt vmcnt(2) lgkmcnt(3)
	v_mfma_f32_32x32x16_bf16 v[0:15], v[192:195], v[216:219], v[0:15]
	v_mfma_f32_32x32x16_bf16 v[16:31], v[192:195], v[220:223], v[16:31]
	v_mfma_f32_32x32x16_bf16 v[32:47], v[192:195], v[224:227], v[32:47]
	ds_read_b128 v[216:219], v54 offset:992
	ds_read_b128 v[220:223], v54 offset:34272
	ds_read_b128 v[224:227], v55 offset:992
	s_waitcnt vmcnt(1) lgkmcnt(3)
	v_mfma_f32_32x32x16_bf16 v[0:15], v[196:199], v[204:207], v[0:15]
	v_mfma_f32_32x32x16_bf16 v[16:31], v[196:199], v[208:211], v[16:31]
	v_mfma_f32_32x32x16_bf16 v[32:47], v[196:199], v[212:215], v[32:47]
	s_waitcnt vmcnt(0) lgkmcnt(0)
	v_mfma_f32_32x32x16_bf16 v[0:15], v[200:203], v[216:219], v[0:15]
	v_mfma_f32_32x32x16_bf16 v[16:31], v[200:203], v[220:223], v[16:31]
	v_mfma_f32_32x32x16_bf16 v[32:47], v[200:203], v[224:227], v[32:47]
	s_movk_i32 s4, 0x48
	v_cmp_gt_u32_e32 vcc, s4, v239
	v_mov_b32_e32 v48, s20
	s_movk_i32 s4, 0x210
	v_lshlrev_b32_e32 v241, 3, v53
	v_mad_u32_u24 v50, v240, s4, v48
	s_and_b32 s6, s24, 0xffffffc0
	v_add_u32_e32 v51, 0x4200, v50
	v_add_u32_e32 v53, 0x8400, v50
	v_cvt_pk_bf16_f32 v48, v0, v1
	v_or_b32_e32 v0, s6, v241
	v_cvt_pk_bf16_f32 v49, v2, v3
	v_add_u32_e32 v1, v50, v0
	v_cvt_pk_bf16_f32 v16, v16, v17
	v_cvt_pk_bf16_f32 v17, v18, v19
	v_add_u32_e32 v2, v51, v0
	v_add_u32_e32 v0, v53, v0
	ds_write_b64 v1, v[48:49]
	ds_write_b64 v2, v[16:17]
	s_and_saveexec_b64 s[4:5], vcc
	v_cvt_pk_bf16_f32 v16, v32, v33
	v_cvt_pk_bf16_f32 v17, v34, v35
	ds_write_b64 v0, v[16:17]
	s_or_b64 exec, exec, s[4:5]
	v_cvt_pk_bf16_f32 v4, v4, v5
	v_cvt_pk_bf16_f32 v5, v6, v7
	ds_write_b64 v1, v[4:5] offset:16
	v_cvt_pk_bf16_f32 v4, v20, v21
	v_cvt_pk_bf16_f32 v5, v22, v23
	ds_write_b64 v2, v[4:5] offset:16
	s_and_saveexec_b64 s[4:5], vcc
	v_cvt_pk_bf16_f32 v4, v36, v37
	v_cvt_pk_bf16_f32 v5, v38, v39
	ds_write_b64 v0, v[4:5] offset:16
	s_or_b64 exec, exec, s[4:5]
	v_cvt_pk_bf16_f32 v4, v8, v9
	v_cvt_pk_bf16_f32 v5, v10, v11
	ds_write_b64 v1, v[4:5] offset:32
	v_cvt_pk_bf16_f32 v4, v24, v25
	v_cvt_pk_bf16_f32 v5, v26, v27
	ds_write_b64 v2, v[4:5] offset:32
	s_and_saveexec_b64 s[4:5], vcc
	v_cvt_pk_bf16_f32 v4, v40, v41
	v_cvt_pk_bf16_f32 v5, v42, v43
	ds_write_b64 v0, v[4:5] offset:32
	s_or_b64 exec, exec, s[4:5]
	v_cvt_pk_bf16_f32 v4, v12, v13
	v_cvt_pk_bf16_f32 v5, v14, v15
	ds_write_b64 v1, v[4:5] offset:48
	v_cvt_pk_bf16_f32 v4, v28, v29
	v_cvt_pk_bf16_f32 v5, v30, v31
	ds_write_b64 v2, v[4:5] offset:48
	s_and_saveexec_b64 s[4:5], vcc
	v_cvt_pk_bf16_f32 v2, v44, v45
	v_cvt_pk_bf16_f32 v3, v46, v47
	ds_write_b64 v0, v[2:3] offset:48
	s_or_b64 exec, exec, s[4:5]
	s_cmp_gt_i32 s1, 1
	s_waitcnt lgkmcnt(0)
	s_barrier
	s_cbranch_scc1 .LBB0_456
	s_or_b32 s4, s6, s23
	v_lshl_or_b32 v0, s4, 6, v235
	v_readlane_b32 s68, v253, 4
	s_ashr_i32 s5, s4, 31
	v_ashrrev_i32_e32 v1, 31, v0
	v_readlane_b32 s74, v253, 10
	s_lshl_b64 s[4:5], s[4:5], 2
	v_lshlrev_b64 v[0:1], 2, v[0:1]
	v_readlane_b32 s70, v253, 6
	v_readlane_b32 s71, v253, 7
	v_readlane_b32 s72, v253, 8
	v_readlane_b32 s73, v253, 9
	v_readlane_b32 s75, v253, 11
	s_add_u32 s4, s74, s4
	v_lshl_add_u64 v[2:3], s[70:71], 0, v[0:1]
	v_lshl_add_u64 v[0:1], s[72:73], 0, v[0:1]
	s_addc_u32 s5, s75, s5
	global_load_dword v1, v[0:1], off
	v_mov_b32_e32 v4, 0
	global_load_dword v0, v233, s[4:5]
	s_mov_b32 s4, 0x42000000
	global_load_dword v2, v[2:3], off
	s_mov_b32 s6, 0
	s_mov_b32 s7, -3
	v_mov_b32_e32 v5, v4
	v_readlane_b32 s69, v253, 5
	v_readlane_b32 s76, v253, 12
	v_readlane_b32 s77, v253, 13
	v_readlane_b32 s78, v253, 14
	v_readlane_b32 s79, v253, 15
	v_readlane_b32 s80, v253, 16
	v_readlane_b32 s81, v253, 17
	v_readlane_b32 s82, v253, 18
	v_readlane_b32 s83, v253, 19
	s_waitcnt vmcnt(1)
	v_mul_f32_e32 v0, 0x3fb8aa3b, v0
	v_exp_f32_e32 v3, v0
	s_waitcnt vmcnt(0)
	v_mul_f32_e32 v0, 0x42000000, v2
	v_mul_f32_e32 v1, v1, v3
	v_mul_f32_e32 v1, 0.15915494, v1
	v_mul_f32_e32 v2, 0x42000000, v1
	v_mul_f32_e32 v0, v0, v3
	v_floor_f32_e32 v2, v2
	v_mul_f32_e32 v0, 0x3fb8aa3b, v0
	v_fma_f32 v1, v1, s4, -v2
	v_exp_f32_e32 v0, v0
	v_cos_f32_e32 v2, v1
	v_sin_f32_e32 v3, v1
	s_lshl_b32 s4, s1, 8
	s_add_i32 s4, s4, 0
	s_add_i32 s4, s4, 0x12800
	v_pk_mul_f32 v[0:1], v[0:1], v[2:3] op_sel_hi:[0,1]
	s_cmp_lt_u32 s24, 64
	v_lshl_add_u32 v6, v235, 1, s4
	s_cselect_b64 s[4:5], -1, 0
	v_pk_mov_b32 v[2:3], v[0:1], v[0:1] op_sel:[1,0]

.LBB0_457:
	s_add_i32 s6, s4, 0x2200
	s_ashr_i32 s7, s6, 31
	v_lshl_add_u64 v[64:65], s[6:7], 1, v[72:73]
	global_load_dwordx4 v[78:81], v[64:65], off
	s_addk_i32 s6, 0xff00
	s_ashr_i32 s7, s6, 31
	v_lshl_add_u64 v[64:65], s[6:7], 1, v[72:73]
	global_load_dwordx4 v[82:85], v[64:65], off
	s_addk_i32 s6, 0xff00
	s_ashr_i32 s7, s6, 31
	v_lshl_add_u64 v[64:65], s[6:7], 1, v[72:73]
	global_load_dwordx4 v[86:89], v[64:65], off
	s_addk_i32 s6, 0xff00
	s_ashr_i32 s7, s6, 31
	v_lshl_add_u64 v[64:65], s[6:7], 1, v[72:73]
	global_load_dwordx4 v[90:93], v[64:65], off
	s_addk_i32 s6, 0xff00
	s_ashr_i32 s7, s6, 31
	v_lshl_add_u64 v[64:65], s[6:7], 1, v[72:73]
	global_load_dwordx4 v[94:97], v[64:65], off
	s_addk_i32 s6, 0xff00
	s_ashr_i32 s7, s6, 31
	v_lshl_add_u64 v[64:65], s[6:7], 1, v[72:73]
	global_load_dwordx4 v[98:101], v[64:65], off
	s_addk_i32 s6, 0xff00
	s_ashr_i32 s7, s6, 31
	v_lshl_add_u64 v[64:65], s[6:7], 1, v[72:73]
	global_load_dwordx4 v[102:105], v[64:65], off
	s_addk_i32 s6, 0xff00
	s_ashr_i32 s7, s6, 31
	v_lshl_add_u64 v[64:65], s[6:7], 1, v[72:73]
	global_load_dwordx4 v[106:109], v[64:65], off
	s_addk_i32 s6, 0xff00
	s_ashr_i32 s7, s6, 31
	v_lshl_add_u64 v[64:65], s[6:7], 1, v[72:73]
	global_load_dwordx4 v[110:113], v[64:65], off
	s_addk_i32 s6, 0xff00
	s_ashr_i32 s7, s6, 31
	v_lshl_add_u64 v[64:65], s[6:7], 1, v[72:73]
	global_load_dwordx4 v[114:117], v[64:65], off
	s_addk_i32 s6, 0xff00
	s_ashr_i32 s7, s6, 31
	v_lshl_add_u64 v[64:65], s[6:7], 1, v[72:73]
	global_load_dwordx4 v[118:121], v[64:65], off
	s_addk_i32 s6, 0xff00
	s_ashr_i32 s7, s6, 31
	v_lshl_add_u64 v[64:65], s[6:7], 1, v[72:73]
	global_load_dwordx4 v[122:125], v[64:65], off
	s_addk_i32 s6, 0xff00
	s_ashr_i32 s7, s6, 31
	v_lshl_add_u64 v[64:65], s[6:7], 1, v[72:73]
	global_load_dwordx4 v[126:129], v[64:65], off
	s_addk_i32 s6, 0xff00
	s_ashr_i32 s7, s6, 31
	v_lshl_add_u64 v[64:65], s[6:7], 1, v[72:73]
	global_load_dwordx4 v[130:133], v[64:65], off
	s_addk_i32 s6, 0xff00
	s_ashr_i32 s7, s6, 31
	v_lshl_add_u64 v[64:65], s[6:7], 1, v[72:73]
	global_load_dwordx4 v[134:137], v[64:65], off
	s_addk_i32 s6, 0xff00
	s_ashr_i32 s7, s6, 31
	v_lshl_add_u64 v[64:65], s[6:7], 1, v[72:73]
	global_load_dwordx4 v[138:141], v[64:65], off
	s_addk_i32 s6, 0xff00
	s_ashr_i32 s7, s6, 31
	v_lshl_add_u64 v[64:65], s[6:7], 1, v[72:73]
	global_load_dwordx4 v[142:145], v[64:65], off
	s_addk_i32 s6, 0xff00
	s_ashr_i32 s7, s6, 31
	v_lshl_add_u64 v[64:65], s[6:7], 1, v[72:73]
	global_load_dwordx4 v[146:149], v[64:65], off
	s_addk_i32 s6, 0xff00
	s_ashr_i32 s7, s6, 31
	v_lshl_add_u64 v[64:65], s[6:7], 1, v[72:73]
	global_load_dwordx4 v[150:153], v[64:65], off
	s_addk_i32 s6, 0xff00
	s_ashr_i32 s7, s6, 31
	v_lshl_add_u64 v[64:65], s[6:7], 1, v[72:73]
	global_load_dwordx4 v[154:157], v[64:65], off
	s_addk_i32 s6, 0xff00
	s_ashr_i32 s7, s6, 31
	v_lshl_add_u64 v[64:65], s[6:7], 1, v[72:73]
	global_load_dwordx4 v[158:161], v[64:65], off
	s_addk_i32 s6, 0xff00
	s_ashr_i32 s7, s6, 31
	v_lshl_add_u64 v[64:65], s[6:7], 1, v[72:73]
	global_load_dwordx4 v[162:165], v[64:65], off
	s_addk_i32 s6, 0xff00
	s_ashr_i32 s7, s6, 31
	v_lshl_add_u64 v[64:65], s[6:7], 1, v[72:73]
	global_load_dwordx4 v[166:169], v[64:65], off
	s_addk_i32 s6, 0xff00
	s_ashr_i32 s7, s6, 31
	v_lshl_add_u64 v[64:65], s[6:7], 1, v[72:73]
	global_load_dwordx4 v[170:173], v[64:65], off
	s_addk_i32 s6, 0xff00
	s_ashr_i32 s7, s6, 31
	v_lshl_add_u64 v[64:65], s[6:7], 1, v[72:73]
	global_load_dwordx4 v[174:177], v[64:65], off
	s_addk_i32 s6, 0xff00
	s_ashr_i32 s7, s6, 31
	v_lshl_add_u64 v[64:65], s[6:7], 1, v[72:73]
	global_load_dwordx4 v[178:181], v[64:65], off
	s_addk_i32 s6, 0xff00
	s_ashr_i32 s7, s6, 31
	v_lshl_add_u64 v[64:65], s[6:7], 1, v[72:73]
	global_load_dwordx4 v[182:185], v[64:65], off
	s_addk_i32 s6, 0xff00
	s_ashr_i32 s7, s6, 31
	v_lshl_add_u64 v[64:65], s[6:7], 1, v[72:73]
	global_load_dwordx4 v[186:189], v[64:65], off
	s_addk_i32 s6, 0xff00
	s_ashr_i32 s7, s6, 31
	v_lshl_add_u64 v[64:65], s[6:7], 1, v[72:73]
	global_load_dwordx4 v[190:193], v[64:65], off
	s_addk_i32 s6, 0xff00
	s_ashr_i32 s7, s6, 31
	v_lshl_add_u64 v[64:65], s[6:7], 1, v[72:73]
	global_load_dwordx4 v[194:197], v[64:65], off
	s_addk_i32 s6, 0xff00
	s_ashr_i32 s7, s6, 31
	v_lshl_add_u64 v[64:65], s[6:7], 1, v[72:73]
	global_load_dwordx4 v[198:201], v[64:65], off
	s_addk_i32 s6, 0xff00
	s_ashr_i32 s7, s6, 31
	v_lshl_add_u64 v[64:65], s[6:7], 1, v[72:73]
	global_load_dwordx4 v[202:205], v[64:65], off
	s_addk_i32 s6, 0xff00
	s_ashr_i32 s7, s6, 31
	v_lshl_add_u64 v[64:65], s[6:7], 1, v[72:73]
	global_load_dwordx4 v[206:209], v[64:65], off
	s_addk_i32 s6, 0xff00
	s_ashr_i32 s7, s6, 31
	v_lshl_add_u64 v[64:65], s[6:7], 1, v[72:73]
	global_load_dwordx4 v[210:213], v[64:65], off
	ds_read_b128 v[214:217], v77 offset:0
	ds_read_b128 v[218:221], v77 offset:33280
	ds_read_b128 v[222:225], v77 offset:32
	ds_read_b128 v[226:229], v77 offset:33312
	s_waitcnt vmcnt(31) lgkmcnt(2)
	v_mfma_f32_32x32x16_bf16 v[48:63], v[86:89], v[214:217], v[48:63]
	v_mfma_f32_32x32x16_bf16 v[32:47], v[86:89], v[218:221], v[32:47]
	v_mfma_f32_32x32x16_bf16 v[16:31], v[78:81], v[214:217], v[16:31]
	v_mfma_f32_32x32x16_bf16 v[0:15], v[78:81], v[218:221], v[0:15]
	ds_read_b128 v[214:217], v77 offset:64
	ds_read_b128 v[218:221], v77 offset:33344
	s_waitcnt vmcnt(30) lgkmcnt(2)
	v_mfma_f32_32x32x16_bf16 v[48:63], v[90:93], v[222:225], v[48:63]
	v_mfma_f32_32x32x16_bf16 v[32:47], v[90:93], v[226:229], v[32:47]
	v_mfma_f32_32x32x16_bf16 v[16:31], v[82:85], v[222:225], v[16:31]
	v_mfma_f32_32x32x16_bf16 v[0:15], v[82:85], v[226:229], v[0:15]
	ds_read_b128 v[222:225], v77 offset:96
	ds_read_b128 v[226:229], v77 offset:33376
	s_waitcnt vmcnt(29) lgkmcnt(2)
	v_mfma_f32_32x32x16_bf16 v[48:63], v[94:97], v[214:217], v[48:63]
	v_mfma_f32_32x32x16_bf16 v[32:47], v[94:97], v[218:221], v[32:47]
	v_mfma_f32_32x32x16_bf16 v[16:31], v[86:89], v[214:217], v[16:31]
	v_mfma_f32_32x32x16_bf16 v[0:15], v[86:89], v[218:221], v[0:15]
	ds_read_b128 v[214:217], v77 offset:128
	ds_read_b128 v[218:221], v77 offset:33408
	s_waitcnt vmcnt(28) lgkmcnt(2)
	v_mfma_f32_32x32x16_bf16 v[48:63], v[98:101], v[222:225], v[48:63]
	v_mfma_f32_32x32x16_bf16 v[32:47], v[98:101], v[226:229], v[32:47]
	v_mfma_f32_32x32x16_bf16 v[16:31], v[90:93], v[222:225], v[16:31]
	v_mfma_f32_32x32x16_bf16 v[0:15], v[90:93], v[226:229], v[0:15]
	ds_read_b128 v[222:225], v77 offset:160
	ds_read_b128 v[226:229], v77 offset:33440
	s_waitcnt vmcnt(27) lgkmcnt(2)
	v_mfma_f32_32x32x16_bf16 v[48:63], v[102:105], v[214:217], v[48:63]
	v_mfma_f32_32x32x16_bf16 v[32:47], v[102:105], v[218:221], v[32:47]
	v_mfma_f32_32x32x16_bf16 v[16:31], v[94:97], v[214:217], v[16:31]
	v_mfma_f32_32x32x16_bf16 v[0:15], v[94:97], v[218:221], v[0:15]
	ds_read_b128 v[214:217], v77 offset:192
	ds_read_b128 v[218:221], v77 offset:33472
	s_waitcnt vmcnt(26) lgkmcnt(2)
	v_mfma_f32_32x32x16_bf16 v[48:63], v[106:109], v[222:225], v[48:63]
	v_mfma_f32_32x32x16_bf16 v[32:47], v[106:109], v[226:229], v[32:47]
	v_mfma_f32_32x32x16_bf16 v[16:31], v[98:101], v[222:225], v[16:31]
	v_mfma_f32_32x32x16_bf16 v[0:15], v[98:101], v[226:229], v[0:15]
	ds_read_b128 v[222:225], v77 offset:224
	ds_read_b128 v[226:229], v77 offset:33504
	s_waitcnt vmcnt(25) lgkmcnt(2)
	v_mfma_f32_32x32x16_bf16 v[48:63], v[110:113], v[214:217], v[48:63]
	v_mfma_f32_32x32x16_bf16 v[32:47], v[110:113], v[218:221], v[32:47]
	v_mfma_f32_32x32x16_bf16 v[16:31], v[102:105], v[214:217], v[16:31]
	v_mfma_f32_32x32x16_bf16 v[0:15], v[102:105], v[218:221], v[0:15]
	ds_read_b128 v[214:217], v77 offset:256
	ds_read_b128 v[218:221], v77 offset:33536
	s_waitcnt vmcnt(24) lgkmcnt(2)
	v_mfma_f32_32x32x16_bf16 v[48:63], v[114:117], v[222:225], v[48:63]
	v_mfma_f32_32x32x16_bf16 v[32:47], v[114:117], v[226:229], v[32:47]
	v_mfma_f32_32x32x16_bf16 v[16:31], v[106:109], v[222:225], v[16:31]
	v_mfma_f32_32x32x16_bf16 v[0:15], v[106:109], v[226:229], v[0:15]
	ds_read_b128 v[222:225], v77 offset:288
	ds_read_b128 v[226:229], v77 offset:33568
	s_waitcnt vmcnt(23) lgkmcnt(2)
	v_mfma_f32_32x32x16_bf16 v[48:63], v[118:121], v[214:217], v[48:63]
	v_mfma_f32_32x32x16_bf16 v[32:47], v[118:121], v[218:221], v[32:47]
	v_mfma_f32_32x32x16_bf16 v[16:31], v[110:113], v[214:217], v[16:31]
	v_mfma_f32_32x32x16_bf16 v[0:15], v[110:113], v[218:221], v[0:15]
	ds_read_b128 v[214:217], v77 offset:320
	ds_read_b128 v[218:221], v77 offset:33600
	s_waitcnt vmcnt(22) lgkmcnt(2)
	v_mfma_f32_32x32x16_bf16 v[48:63], v[122:125], v[222:225], v[48:63]
	v_mfma_f32_32x32x16_bf16 v[32:47], v[122:125], v[226:229], v[32:47]
	v_mfma_f32_32x32x16_bf16 v[16:31], v[114:117], v[222:225], v[16:31]
	v_mfma_f32_32x32x16_bf16 v[0:15], v[114:117], v[226:229], v[0:15]
	ds_read_b128 v[222:225], v77 offset:352
	ds_read_b128 v[226:229], v77 offset:33632
	s_waitcnt vmcnt(21) lgkmcnt(2)
	v_mfma_f32_32x32x16_bf16 v[48:63], v[126:129], v[214:217], v[48:63]
	v_mfma_f32_32x32x16_bf16 v[32:47], v[126:129], v[218:221], v[32:47]
	v_mfma_f32_32x32x16_bf16 v[16:31], v[118:121], v[214:217], v[16:31]
	v_mfma_f32_32x32x16_bf16 v[0:15], v[118:121], v[218:221], v[0:15]
	ds_read_b128 v[214:217], v77 offset:384
	ds_read_b128 v[218:221], v77 offset:33664
	s_waitcnt vmcnt(20) lgkmcnt(2)
	v_mfma_f32_32x32x16_bf16 v[48:63], v[130:133], v[222:225], v[48:63]
	v_mfma_f32_32x32x16_bf16 v[32:47], v[130:133], v[226:229], v[32:47]
	v_mfma_f32_32x32x16_bf16 v[16:31], v[122:125], v[222:225], v[16:31]
	v_mfma_f32_32x32x16_bf16 v[0:15], v[122:125], v[226:229], v[0:15]
	ds_read_b128 v[222:225], v77 offset:416
	ds_read_b128 v[226:229], v77 offset:33696
	s_waitcnt vmcnt(19) lgkmcnt(2)
	v_mfma_f32_32x32x16_bf16 v[48:63], v[134:137], v[214:217], v[48:63]
	v_mfma_f32_32x32x16_bf16 v[32:47], v[134:137], v[218:221], v[32:47]
	v_mfma_f32_32x32x16_bf16 v[16:31], v[126:129], v[214:217], v[16:31]
	v_mfma_f32_32x32x16_bf16 v[0:15], v[126:129], v[218:221], v[0:15]
	ds_read_b128 v[214:217], v77 offset:448
	ds_read_b128 v[218:221], v77 offset:33728
	s_waitcnt vmcnt(18) lgkmcnt(2)
	v_mfma_f32_32x32x16_bf16 v[48:63], v[138:141], v[222:225], v[48:63]
	v_mfma_f32_32x32x16_bf16 v[32:47], v[138:141], v[226:229], v[32:47]
	v_mfma_f32_32x32x16_bf16 v[16:31], v[130:133], v[222:225], v[16:31]
	v_mfma_f32_32x32x16_bf16 v[0:15], v[130:133], v[226:229], v[0:15]
	ds_read_b128 v[222:225], v77 offset:480
	ds_read_b128 v[226:229], v77 offset:33760
	s_waitcnt vmcnt(17) lgkmcnt(2)
	v_mfma_f32_32x32x16_bf16 v[48:63], v[142:145], v[214:217], v[48:63]
	v_mfma_f32_32x32x16_bf16 v[32:47], v[142:145], v[218:221], v[32:47]
	v_mfma_f32_32x32x16_bf16 v[16:31], v[134:137], v[214:217], v[16:31]
	v_mfma_f32_32x32x16_bf16 v[0:15], v[134:137], v[218:221], v[0:15]
	ds_read_b128 v[214:217], v77 offset:512
	ds_read_b128 v[218:221], v77 offset:33792
	s_waitcnt vmcnt(16) lgkmcnt(2)
	v_mfma_f32_32x32x16_bf16 v[48:63], v[146:149], v[222:225], v[48:63]
	v_mfma_f32_32x32x16_bf16 v[32:47], v[146:149], v[226:229], v[32:47]
	v_mfma_f32_32x32x16_bf16 v[16:31], v[138:141], v[222:225], v[16:31]
	v_mfma_f32_32x32x16_bf16 v[0:15], v[138:141], v[226:229], v[0:15]
	ds_read_b128 v[222:225], v77 offset:544
	ds_read_b128 v[226:229], v77 offset:33824
	s_waitcnt vmcnt(15) lgkmcnt(2)
	v_mfma_f32_32x32x16_bf16 v[48:63], v[150:153], v[214:217], v[48:63]
	v_mfma_f32_32x32x16_bf16 v[32:47], v[150:153], v[218:221], v[32:47]
	v_mfma_f32_32x32x16_bf16 v[16:31], v[142:145], v[214:217], v[16:31]
	v_mfma_f32_32x32x16_bf16 v[0:15], v[142:145], v[218:221], v[0:15]
	ds_read_b128 v[214:217], v77 offset:576
	ds_read_b128 v[218:221], v77 offset:33856
	s_waitcnt vmcnt(14) lgkmcnt(2)
	v_mfma_f32_32x32x16_bf16 v[48:63], v[154:157], v[222:225], v[48:63]
	v_mfma_f32_32x32x16_bf16 v[32:47], v[154:157], v[226:229], v[32:47]
	v_mfma_f32_32x32x16_bf16 v[16:31], v[146:149], v[222:225], v[16:31]
	v_mfma_f32_32x32x16_bf16 v[0:15], v[146:149], v[226:229], v[0:15]
	ds_read_b128 v[222:225], v77 offset:608
	ds_read_b128 v[226:229], v77 offset:33888
	s_waitcnt vmcnt(13) lgkmcnt(2)
	v_mfma_f32_32x32x16_bf16 v[48:63], v[158:161], v[214:217], v[48:63]
	v_mfma_f32_32x32x16_bf16 v[32:47], v[158:161], v[218:221], v[32:47]
	v_mfma_f32_32x32x16_bf16 v[16:31], v[150:153], v[214:217], v[16:31]
	v_mfma_f32_32x32x16_bf16 v[0:15], v[150:153], v[218:221], v[0:15]
	ds_read_b128 v[214:217], v77 offset:640
	ds_read_b128 v[218:221], v77 offset:33920
	s_waitcnt vmcnt(12) lgkmcnt(2)
	v_mfma_f32_32x32x16_bf16 v[48:63], v[162:165], v[222:225], v[48:63]
	v_mfma_f32_32x32x16_bf16 v[32:47], v[162:165], v[226:229], v[32:47]
	v_mfma_f32_32x32x16_bf16 v[16:31], v[154:157], v[222:225], v[16:31]
	v_mfma_f32_32x32x16_bf16 v[0:15], v[154:157], v[226:229], v[0:15]
	ds_read_b128 v[222:225], v77 offset:672
	ds_read_b128 v[226:229], v77 offset:33952
	s_waitcnt vmcnt(11) lgkmcnt(2)
	v_mfma_f32_32x32x16_bf16 v[48:63], v[166:169], v[214:217], v[48:63]
	v_mfma_f32_32x32x16_bf16 v[32:47], v[166:169], v[218:221], v[32:47]
	v_mfma_f32_32x32x16_bf16 v[16:31], v[158:161], v[214:217], v[16:31]
	v_mfma_f32_32x32x16_bf16 v[0:15], v[158:161], v[218:221], v[0:15]
	ds_read_b128 v[214:217], v77 offset:704
	ds_read_b128 v[218:221], v77 offset:33984
	s_waitcnt vmcnt(10) lgkmcnt(2)
	v_mfma_f32_32x32x16_bf16 v[48:63], v[170:173], v[222:225], v[48:63]
	v_mfma_f32_32x32x16_bf16 v[32:47], v[170:173], v[226:229], v[32:47]
	v_mfma_f32_32x32x16_bf16 v[16:31], v[162:165], v[222:225], v[16:31]
	v_mfma_f32_32x32x16_bf16 v[0:15], v[162:165], v[226:229], v[0:15]
	ds_read_b128 v[222:225], v77 offset:736
	ds_read_b128 v[226:229], v77 offset:34016
	s_waitcnt vmcnt(9) lgkmcnt(2)
	v_mfma_f32_32x32x16_bf16 v[48:63], v[174:177], v[214:217], v[48:63]
	v_mfma_f32_32x32x16_bf16 v[32:47], v[174:177], v[218:221], v[32:47]
	v_mfma_f32_32x32x16_bf16 v[16:31], v[166:169], v[214:217], v[16:31]
	v_mfma_f32_32x32x16_bf16 v[0:15], v[166:169], v[218:221], v[0:15]
	ds_read_b128 v[214:217], v77 offset:768
	ds_read_b128 v[218:221], v77 offset:34048
	s_waitcnt vmcnt(8) lgkmcnt(2)
	v_mfma_f32_32x32x16_bf16 v[48:63], v[178:181], v[222:225], v[48:63]
	v_mfma_f32_32x32x16_bf16 v[32:47], v[178:181], v[226:229], v[32:47]
	v_mfma_f32_32x32x16_bf16 v[16:31], v[170:173], v[222:225], v[16:31]
	v_mfma_f32_32x32x16_bf16 v[0:15], v[170:173], v[226:229], v[0:15]
	ds_read_b128 v[222:225], v77 offset:800
	ds_read_b128 v[226:229], v77 offset:34080
	s_waitcnt vmcnt(7) lgkmcnt(2)
	v_mfma_f32_32x32x16_bf16 v[48:63], v[182:185], v[214:217], v[48:63]
	v_mfma_f32_32x32x16_bf16 v[32:47], v[182:185], v[218:221], v[32:47]
	v_mfma_f32_32x32x16_bf16 v[16:31], v[174:177], v[214:217], v[16:31]
	v_mfma_f32_32x32x16_bf16 v[0:15], v[174:177], v[218:221], v[0:15]
	ds_read_b128 v[214:217], v77 offset:832
	ds_read_b128 v[218:221], v77 offset:34112
	s_waitcnt vmcnt(6) lgkmcnt(2)
	v_mfma_f32_32x32x16_bf16 v[48:63], v[186:189], v[222:225], v[48:63]
	v_mfma_f32_32x32x16_bf16 v[32:47], v[186:189], v[226:229], v[32:47]
	v_mfma_f32_32x32x16_bf16 v[16:31], v[178:181], v[222:225], v[16:31]
	v_mfma_f32_32x32x16_bf16 v[0:15], v[178:181], v[226:229], v[0:15]
	ds_read_b128 v[222:225], v77 offset:864
	ds_read_b128 v[226:229], v77 offset:34144
	s_waitcnt vmcnt(5) lgkmcnt(2)
	v_mfma_f32_32x32x16_bf16 v[48:63], v[190:193], v[214:217], v[48:63]
	v_mfma_f32_32x32x16_bf16 v[32:47], v[190:193], v[218:221], v[32:47]
	v_mfma_f32_32x32x16_bf16 v[16:31], v[182:185], v[214:217], v[16:31]
	v_mfma_f32_32x32x16_bf16 v[0:15], v[182:185], v[218:221], v[0:15]
	ds_read_b128 v[214:217], v77 offset:896
	ds_read_b128 v[218:221], v77 offset:34176
	s_waitcnt vmcnt(4) lgkmcnt(2)
	v_mfma_f32_32x32x16_bf16 v[48:63], v[194:197], v[222:225], v[48:63]
	v_mfma_f32_32x32x16_bf16 v[32:47], v[194:197], v[226:229], v[32:47]
	v_mfma_f32_32x32x16_bf16 v[16:31], v[186:189], v[222:225], v[16:31]
	v_mfma_f32_32x32x16_bf16 v[0:15], v[186:189], v[226:229], v[0:15]
	ds_read_b128 v[222:225], v77 offset:928
	ds_read_b128 v[226:229], v77 offset:34208
	s_waitcnt vmcnt(3) lgkmcnt(2)
	v_mfma_f32_32x32x16_bf16 v[48:63], v[198:201], v[214:217], v[48:63]
	v_mfma_f32_32x32x16_bf16 v[32:47], v[198:201], v[218:221], v[32:47]
	v_mfma_f32_32x32x16_bf16 v[16:31], v[190:193], v[214:217], v[16:31]
	v_mfma_f32_32x32x16_bf16 v[0:15], v[190:193], v[218:221], v[0:15]
	ds_read_b128 v[214:217], v77 offset:960
	ds_read_b128 v[218:221], v77 offset:34240
	s_waitcnt vmcnt(2) lgkmcnt(2)
	v_mfma_f32_32x32x16_bf16 v[48:63], v[202:205], v[222:225], v[48:63]
	v_mfma_f32_32x32x16_bf16 v[32:47], v[202:205], v[226:229], v[32:47]
	v_mfma_f32_32x32x16_bf16 v[16:31], v[194:197], v[222:225], v[16:31]
	v_mfma_f32_32x32x16_bf16 v[0:15], v[194:197], v[226:229], v[0:15]
	ds_read_b128 v[222:225], v77 offset:992
	ds_read_b128 v[226:229], v77 offset:34272
	s_waitcnt vmcnt(1) lgkmcnt(2)
	v_mfma_f32_32x32x16_bf16 v[48:63], v[206:209], v[214:217], v[48:63]
	v_mfma_f32_32x32x16_bf16 v[32:47], v[206:209], v[218:221], v[32:47]
	v_mfma_f32_32x32x16_bf16 v[16:31], v[198:201], v[214:217], v[16:31]
	v_mfma_f32_32x32x16_bf16 v[0:15], v[198:201], v[218:221], v[0:15]
	s_waitcnt vmcnt(0) lgkmcnt(0)
	v_mfma_f32_32x32x16_bf16 v[48:63], v[210:213], v[222:225], v[48:63]
	v_mfma_f32_32x32x16_bf16 v[32:47], v[210:213], v[226:229], v[32:47]
	v_mfma_f32_32x32x16_bf16 v[16:31], v[202:205], v[222:225], v[16:31]
	v_mfma_f32_32x32x16_bf16 v[0:15], v[202:205], v[226:229], v[0:15]
	s_lshl_b32 s6, s1, 1
	s_lshl_b32 s4, s1, 2
	s_lshl_b32 s5, s23, 18
	s_ashr_i32 s7, s6, 31
	s_add_u32 s5, s40, s5
	s_addc_u32 s12, s41, 0
	s_lshl_b64 s[6:7], s[6:7], 14
	s_add_u32 s6, s5, s6
	s_addc_u32 s7, s12, s7
	v_lshlrev_b32_e32 v64, 1, v75
	v_mov_b32_e32 v65, v233
	v_lshl_add_u64 v[64:65], s[6:7], 0, v[64:65]
	v_lshl_add_u64 v[148:149], v[64:65], 0, v[232:233]
	global_load_dwordx4 v[68:71], v[148:149], off
	s_movk_i32 s5, 0x5000
	v_add_co_u32_e32 v192, vcc, s5, v148
	s_movk_i32 s5, 0x4000
	s_nop 0
	v_addc_co_u32_e32 v193, vcc, 0, v149, vcc
	v_add_co_u32_e32 v88, vcc, s5, v148
	v_mul_u32_u24_e32 v64, 0x210, v76
	s_nop 0
	v_addc_co_u32_e32 v89, vcc, 0, v149, vcc
	s_movk_i32 s5, 0x2000
	v_add3_u32 v232, s20, v64, v74
	v_add_co_u32_e32 v108, vcc, s5, v148
	ds_read_b128 v[72:75], v232
	ds_read_b128 v[80:83], v232 offset:32
	ds_read_b128 v[64:67], v232 offset:16896
	ds_read_b128 v[84:87], v232 offset:16960
	v_addc_co_u32_e32 v109, vcc, 0, v149, vcc
	s_movk_i32 s5, 0x1000
	v_add_co_u32_e32 v110, vcc, s5, v148
	s_movk_i32 s5, 0x3000
	s_nop 0
	v_addc_co_u32_e32 v111, vcc, 0, v149, vcc
	v_add_co_u32_e32 v132, vcc, s5, v148
	global_load_dwordx4 v[100:103], v[88:89], off offset:1024
	global_load_dwordx4 v[96:99], v[88:89], off offset:2048
	v_addc_co_u32_e32 v133, vcc, 0, v149, vcc
	global_load_dwordx4 v[224:227], v[132:133], off offset:3072
	global_load_dwordx4 v[188:191], v[110:111], off offset:3072
	global_load_dwordx4 v[212:215], v[132:133], off
	global_load_dwordx4 v[216:219], v[132:133], off offset:1024
	global_load_dwordx4 v[220:223], v[132:133], off offset:2048
	global_load_dwordx4 v[184:187], v[108:109], off
	global_load_dwordx4 v[128:131], v[110:111], off offset:1024
	global_load_dwordx4 v[144:147], v[110:111], off offset:2048
	global_load_dwordx4 v[204:207], v[108:109], off offset:2048
	global_load_dwordx4 v[208:211], v[108:109], off offset:3072
	ds_read_b128 v[104:107], v232 offset:128
	ds_read_b128 v[200:203], v232 offset:160
	global_load_dwordx4 v[88:91], v[88:89], off offset:3072
	ds_read_b128 v[140:143], v232 offset:192
	ds_read_b128 v[124:127], v232 offset:224
	ds_read_b128 v[120:123], v232 offset:256
	ds_read_b128 v[116:119], v232 offset:288
	ds_read_b128 v[112:115], v232 offset:320
	ds_read_b128 v[164:167], v232 offset:384
	ds_read_b128 v[156:159], v232 offset:416
	s_movk_i32 s5, 0x7000
	v_add_co_u32_e32 v236, vcc, s5, v148
	s_movk_i32 s5, 0x6000
	s_nop 0
	v_addc_co_u32_e32 v237, vcc, 0, v149, vcc
	v_add_co_u32_e32 v194, vcc, s5, v148
	ds_read_b128 v[152:155], v232 offset:448
	ds_read_b128 v[168:171], v232 offset:480
	v_addc_co_u32_e32 v195, vcc, 0, v149, vcc
	s_lshl_b32 s1, s1, 13
	s_add_i32 s5, s1, 0
	s_ashr_i32 s1, s0, 31
	s_lshl_b64 s[0:1], s[0:1], 11
	s_ashr_i32 s6, s4, 31
	s_add_u32 s0, s0, s4
	s_addc_u32 s1, s1, s6
	s_lshl_b32 s4, s23, 5
	s_add_u32 s6, s42, s4
	s_addc_u32 s7, s43, 0
	s_or_b32 s4, s0, 1
	s_add_i32 s22, s22, s94
	s_add_i32 s21, s21, s94
	s_waitcnt vmcnt(13) lgkmcnt(14)
	v_mfma_f32_32x32x16_bf16 v[48:63], v[68:71], v[72:75], v[48:63]
	global_load_dwordx4 v[76:79], v[148:149], off offset:1024
	ds_read_b128 v[132:135], v232 offset:17088
	global_load_dwordx4 v[136:139], v[192:193], off offset:1024
	ds_read_b128 v[92:95], v232 offset:96
	global_load_dwordx4 v[228:231], v[108:109], off offset:1024
	s_waitcnt lgkmcnt(14)
	v_mfma_f32_32x32x16_bf16 v[32:47], v[68:71], v[64:67], v[32:47]
	global_load_dwordx4 v[68:71], v[192:193], off offset:-4096
	s_waitcnt vmcnt(0)
	v_mfma_f32_32x32x16_bf16 v[16:31], v[68:71], v[72:75], v[16:31]
	ds_read_b128 v[72:75], v232 offset:16928
	v_mfma_f32_32x32x16_bf16 v[48:63], v[76:79], v[80:83], v[48:63]
	s_waitcnt lgkmcnt(0)
	v_mfma_f32_32x32x16_bf16 v[32:47], v[76:79], v[72:75], v[32:47]
	global_load_dwordx4 v[76:79], v[148:149], off offset:2048
	v_mfma_f32_32x32x16_bf16 v[16:31], v[100:103], v[80:83], v[16:31]
	ds_read_b128 v[80:83], v232 offset:64
	s_waitcnt vmcnt(0) lgkmcnt(0)
	v_mfma_f32_32x32x16_bf16 v[48:63], v[76:79], v[80:83], v[48:63]
	v_mfma_f32_32x32x16_bf16 v[16:31], v[96:99], v[80:83], v[16:31]
	global_load_dwordx4 v[80:83], v[148:149], off offset:3072
	s_waitcnt vmcnt(0)
	v_mfma_f32_32x32x16_bf16 v[48:63], v[80:83], v[92:95], v[48:63]
	v_mfma_f32_32x32x16_bf16 v[16:31], v[88:91], v[92:95], v[16:31]
	global_load_dwordx4 v[92:95], v[108:109], off offset:-4096
	ds_read_b128 v[108:111], v232 offset:352
	v_mfma_f32_32x32x16_bf16 v[32:47], v[76:79], v[84:87], v[32:47]
	ds_read_b128 v[76:79], v232 offset:16992
	s_waitcnt lgkmcnt(0)
	v_mfma_f32_32x32x16_bf16 v[32:47], v[80:83], v[76:79], v[32:47]
	ds_read_b128 v[80:83], v232 offset:17024
	v_mfma_f32_32x32x16_bf16 v[0:15], v[68:71], v[64:67], v[0:15]
	v_mfma_f32_32x32x16_bf16 v[0:15], v[100:103], v[72:75], v[0:15]
	v_mfma_f32_32x32x16_bf16 v[0:15], v[96:99], v[84:87], v[0:15]
	s_waitcnt vmcnt(0)
	v_mfma_f32_32x32x16_bf16 v[48:63], v[92:95], v[104:107], v[48:63]
	s_waitcnt lgkmcnt(0)
	v_mfma_f32_32x32x16_bf16 v[32:47], v[92:95], v[80:83], v[32:47]
	global_load_dwordx4 v[92:95], v[192:193], off
	v_mfma_f32_32x32x16_bf16 v[48:63], v[128:131], v[200:203], v[48:63]
	v_mfma_f32_32x32x16_bf16 v[48:63], v[144:147], v[140:143], v[48:63]
	v_mfma_f32_32x32x16_bf16 v[48:63], v[188:191], v[124:127], v[48:63]
	v_mfma_f32_32x32x16_bf16 v[48:63], v[184:187], v[120:123], v[48:63]
	v_mfma_f32_32x32x16_bf16 v[48:63], v[228:231], v[116:119], v[48:63]
	v_mfma_f32_32x32x16_bf16 v[48:63], v[204:207], v[112:115], v[48:63]
	s_waitcnt vmcnt(0)
	v_mfma_f32_32x32x16_bf16 v[16:31], v[92:95], v[104:107], v[16:31]
	ds_read_b128 v[104:107], v232 offset:17056
	v_mfma_f32_32x32x16_bf16 v[48:63], v[208:211], v[108:111], v[48:63]
	s_waitcnt lgkmcnt(0)
	v_mfma_f32_32x32x16_bf16 v[32:47], v[128:131], v[104:107], v[32:47]
	global_load_dwordx4 v[128:131], v[236:237], off offset:-4096
	v_mfma_f32_32x32x16_bf16 v[48:63], v[212:215], v[164:167], v[48:63]
	v_mfma_f32_32x32x16_bf16 v[32:47], v[144:147], v[132:135], v[32:47]
	global_load_dwordx4 v[144:147], v[194:195], off offset:3072
	ds_read_b128 v[180:183], v232 offset:17120
	ds_read_b128 v[176:179], v232 offset:17152
	ds_read_b128 v[172:175], v232 offset:17184
	ds_read_b128 v[160:163], v232 offset:17216
	ds_read_b128 v[148:151], v232 offset:17248
	v_mfma_f32_32x32x16_bf16 v[48:63], v[216:219], v[156:159], v[48:63]
	s_waitcnt lgkmcnt(4)
	v_mfma_f32_32x32x16_bf16 v[32:47], v[188:191], v[180:183], v[32:47]
	v_mfma_f32_32x32x16_bf16 v[48:63], v[220:223], v[152:155], v[48:63]
	s_waitcnt lgkmcnt(3)
	v_mfma_f32_32x32x16_bf16 v[32:47], v[184:187], v[176:179], v[32:47]
	v_mfma_f32_32x32x16_bf16 v[48:63], v[224:227], v[168:171], v[48:63]
	s_waitcnt lgkmcnt(2)
	v_mfma_f32_32x32x16_bf16 v[32:47], v[228:231], v[172:175], v[32:47]
	s_nop 9
	v_mul_f32_e32 v188, 0x3d372713, v48
	v_mul_f32_e32 v196, 0x3fcc422a, v48
	v_fma_f32 v188, v48, v188, 1.0
	v_mul_f32_e32 v188, v196, v188
	v_mul_f32_e32 v188, 0xbfb8aa3b, v188
	v_exp_f32_e32 v238, v188
	global_load_dwordx4 v[196:199], v[192:193], off offset:2048
	global_load_dwordx4 v[188:191], v[192:193], off offset:3072
	s_waitcnt lgkmcnt(1)
	v_mfma_f32_32x32x16_bf16 v[32:47], v[204:207], v[160:163], v[32:47]
	v_mul_f32_e32 v193, 0x3d372713, v49
	v_mul_f32_e32 v192, 0x3fcc422a, v49
	v_fma_f32 v193, v49, v193, 1.0
	v_mul_f32_e32 v242, v192, v193
	v_mul_f32_e32 v242, 0xbfb8aa3b, v242
	v_mul_f32_e32 v229, 0x3d372713, v50
	v_exp_f32_e32 v242, v242
	v_mul_f32_e32 v228, 0x3fcc422a, v50
	v_fma_f32 v229, v50, v229, 1.0
	v_mul_f32_e32 v230, 0x3d372713, v51
	v_mul_f32_e32 v229, v228, v229
	v_mul_f32_e32 v228, 0x3fcc422a, v51
	v_fma_f32 v230, v51, v230, 1.0
	v_add_f32_e32 v238, 1.0, v238
	v_mul_f32_e32 v230, v228, v230
	v_mul_f32_e32 v229, 0xbfb8aa3b, v229
	v_rcp_f32_e32 v228, v238
	v_exp_f32_e32 v238, v229
	v_mul_f32_e32 v229, 0xbfb8aa3b, v230
	s_waitcnt lgkmcnt(0)
	v_mfma_f32_32x32x16_bf16 v[32:47], v[208:211], v[148:151], v[32:47]
	v_add_f32_e32 v231, 1.0, v242
	v_exp_f32_e32 v242, v229
	ds_read_b128 v[208:211], v232 offset:17280
	v_rcp_f32_e32 v229, v231
	v_add_f32_e32 v230, 1.0, v238
	v_add_f32_e32 v231, 1.0, v242
	v_rcp_f32_e32 v230, v230
	v_rcp_f32_e32 v231, v231
	s_waitcnt lgkmcnt(0)
	v_mfma_f32_32x32x16_bf16 v[32:47], v[212:215], v[208:211], v[32:47]
	v_mul_f32_e64 v48, v48, v228
	v_mul_f32_e64 v49, v49, v229
	ds_read_b128 v[212:215], v232 offset:17312
	v_cvt_pk_bf16_f32 v228, v48, v49
	v_mul_f32_e64 v48, v50, v230
	v_mul_f32_e64 v49, v51, v231
	v_mul_f32_e32 v50, 0x3d372713, v53
	v_cvt_pk_bf16_f32 v229, v48, v49
	v_mul_f32_e32 v49, 0x3d372713, v52
	v_mul_f32_e32 v48, 0x3fcc422a, v52
	v_fma_f32 v49, v52, v49, 1.0
	v_mul_f32_e32 v48, v48, v49
	v_mul_f32_e32 v49, 0x3fcc422a, v53
	v_fma_f32 v50, v53, v50, 1.0
	v_mul_f32_e32 v48, 0xbfb8aa3b, v48
	v_mul_f32_e32 v49, v49, v50
	v_exp_f32_e32 v48, v48
	v_mul_f32_e32 v49, 0xbfb8aa3b, v49
	v_exp_f32_e32 v49, v49
	s_waitcnt lgkmcnt(0)
	v_mfma_f32_32x32x16_bf16 v[32:47], v[216:219], v[212:215], v[32:47]
	v_mul_f32_e32 v51, 0x3d372713, v54
	v_mul_f32_e32 v50, 0x3fcc422a, v54
	v_fma_f32 v51, v54, v51, 1.0
	v_add_f32_e32 v48, 1.0, v48
	v_mul_f32_e32 v50, v50, v51
	ds_read_b128 v[216:219], v232 offset:17344
	v_rcp_f32_e32 v230, v48
	v_add_f32_e32 v48, 1.0, v49
	v_mul_f32_e32 v49, 0xbfb8aa3b, v50
	v_mul_f32_e32 v50, 0x3d372713, v55
	v_exp_f32_e32 v238, v49
	v_mul_f32_e32 v49, 0x3fcc422a, v55
	v_fma_f32 v50, v55, v50, 1.0
	global_load_dwordx4 v[184:187], v[194:195], off offset:1024
	global_load_dwordx4 v[204:207], v[236:237], off
	v_mul_f32_e32 v49, v49, v50
	v_mul_f32_e32 v49, 0xbfb8aa3b, v49
	s_waitcnt lgkmcnt(0)
	v_mfma_f32_32x32x16_bf16 v[32:47], v[220:223], v[216:219], v[32:47]
	v_exp_f32_e32 v221, v49
	v_rcp_f32_e32 v231, v48
	v_add_f32_e32 v220, 1.0, v238
	v_rcp_f32_e32 v220, v220
	v_add_f32_e32 v221, 1.0, v221
	v_rcp_f32_e32 v221, v221
	global_load_dwordx4 v[192:195], v[194:195], off offset:2048
	ds_read_b128 v[48:51], v232 offset:17376
	v_pk_mul_f32 v[52:53], v[52:53], v[230:231]
	v_lshlrev_b32_e32 v230, 5, v240
	v_cvt_pk_bf16_f32 v242, v52, v53
	v_pk_mul_f32 v[52:53], v[54:55], v[220:221]
	v_add3_u32 v230, s5, v230, v241
	v_cvt_pk_bf16_f32 v243, v52, v53
	s_waitcnt lgkmcnt(0)
	v_mfma_f32_32x32x16_bf16 v[32:47], v[224:227], v[48:51], v[32:47]
	global_load_dwordx4 v[224:227], v[236:237], off offset:1024
	global_load_dwordx4 v[220:223], v[236:237], off offset:2048
	global_load_dwordx4 v[52:55], v[236:237], off offset:3072
	s_barrier
	ds_write2_b64 v230, v[228:229], v[242:243] offset1:2
	v_mul_f32_e32 v228, 0x3d372713, v56
	v_fma_f32 v228, v56, v228, 1.0
	v_mul_f32_e32 v229, 0x3fcc422a, v56
	v_mul_f32_e32 v228, v229, v228
	v_mul_f32_e32 v228, 0xbfb8aa3b, v228
	v_exp_f32_e32 v228, v228
	v_mfma_f32_32x32x16_bf16 v[16:31], v[136:139], v[200:203], v[16:31]
	v_mul_f32_e32 v201, 0x3d372713, v57
	v_mul_f32_e32 v200, 0x3fcc422a, v57
	v_fma_f32 v201, v57, v201, 1.0
	v_mul_f32_e32 v203, 0x3d372713, v58
	v_mul_f32_e32 v200, v200, v201
	v_mul_f32_e32 v202, 0x3fcc422a, v58
	v_fma_f32 v203, v58, v203, 1.0
	v_mul_f32_e32 v200, 0xbfb8aa3b, v200
	v_mul_f32_e32 v202, v202, v203
	v_mul_f32_e32 v203, 0x3d372713, v59
	v_exp_f32_e32 v201, v200
	v_add_f32_e32 v200, 1.0, v228
	v_fma_f32 v203, v59, v203, 1.0
	v_mul_f32_e32 v228, 0x3fcc422a, v59
	v_mul_f32_e32 v203, v228, v203
	v_mul_f32_e32 v202, 0xbfb8aa3b, v202
	v_mul_f32_e32 v203, 0xbfb8aa3b, v203
	v_exp_f32_e32 v202, v202
	v_exp_f32_e32 v203, v203
	v_add_f32_e32 v201, 1.0, v201
	v_rcp_f32_e32 v200, v200
	v_rcp_f32_e32 v201, v201
	v_add_f32_e32 v202, 1.0, v202
	v_add_f32_e32 v203, 1.0, v203
	v_rcp_f32_e32 v202, v202
	v_rcp_f32_e32 v203, v203
	v_pk_mul_f32 v[56:57], v[56:57], v[200:201]
	s_waitcnt vmcnt(7)
	v_mfma_f32_32x32x16_bf16 v[16:31], v[196:199], v[140:143], v[16:31]
	v_cvt_pk_bf16_f32 v200, v56, v57
	v_mul_f32_e64 v56, v58, v202
	v_mul_f32_e64 v57, v59, v203
	v_mul_f32_e32 v58, 0x3fcc422a, v61
	v_cvt_pk_bf16_f32 v201, v56, v57
	v_mul_f32_e32 v57, 0x3d372713, v60
	v_mul_f32_e32 v56, 0x3fcc422a, v60
	v_fma_f32 v57, v60, v57, 1.0
	v_mul_f32_e32 v56, v56, v57
	v_mul_f32_e32 v57, 0x3d372713, v61
	v_fma_f32 v57, v61, v57, 1.0
	v_mul_f32_e32 v57, v58, v57
	v_mul_f32_e32 v56, 0xbfb8aa3b, v56
	v_exp_f32_e32 v59, v56
	v_mul_f32_e32 v56, 0xbfb8aa3b, v57
	v_exp_f32_e32 v57, v56
	v_lshlrev_b32_e32 v58, 5, v239
	v_add3_u32 v56, s5, v58, v241
	v_add_f32_e32 v58, 1.0, v59
	v_add_f32_e32 v57, 1.0, v57
	v_rcp_f32_e32 v59, v57
	v_mul_f32_e32 v57, 0x3d372713, v62
	v_rcp_f32_e32 v58, v58
	v_fma_f32 v57, v62, v57, 1.0
	v_mul_f32_e32 v202, 0x3fcc422a, v62
	v_mul_f32_e32 v57, v202, v57
	v_mul_f32_e32 v202, 0x3d372713, v63
	v_fma_f32 v202, v63, v202, 1.0
	v_mul_f32_e32 v203, 0x3fcc422a, v63
	v_mul_f32_e32 v202, v203, v202
	v_mul_f32_e32 v57, 0xbfb8aa3b, v57
	v_pk_mul_f32 v[58:59], v[60:61], v[58:59]
	v_exp_f32_e32 v57, v57
	v_mul_f32_e32 v60, 0xbfb8aa3b, v202
	v_exp_f32_e32 v61, v60
	v_cvt_pk_bf16_f32 v58, v58, v59
	v_add_f32_e32 v57, 1.0, v57
	v_rcp_f32_e32 v60, v57
	v_add_f32_e32 v57, 1.0, v61
	v_mul_f32_e32 v61, 0x3d372713, v32
	v_mul_f32_e32 v59, 0x3fcc422a, v32
	v_fma_f32 v61, v32, v61, 1.0
	v_mul_f32_e32 v140, 0x3d372713, v33
	v_mul_f32_e32 v59, v59, v61
	v_mul_f32_e32 v61, 0x3fcc422a, v33
	v_fma_f32 v140, v33, v140, 1.0
	v_mul_f32_e32 v59, 0xbfb8aa3b, v59
	v_mul_f32_e32 v61, v61, v140
	v_exp_f32_e32 v59, v59
	v_mul_f32_e32 v61, 0xbfb8aa3b, v61
	v_exp_f32_e32 v141, v61
	v_rcp_f32_e32 v61, v57
	v_add_f32_e32 v57, 1.0, v59
	v_rcp_f32_e32 v140, v57
	v_add_f32_e32 v57, 1.0, v141
	v_rcp_f32_e32 v141, v57
	v_pk_mul_f32 v[60:61], v[62:63], v[60:61]
	s_waitcnt vmcnt(6)
	v_mfma_f32_32x32x16_bf16 v[16:31], v[188:191], v[124:127], v[16:31]
	v_cvt_pk_bf16_f32 v59, v60, v61
	v_mul_f32_e64 v32, v32, v140
	v_mul_f32_e64 v33, v33, v141
	v_mul_f32_e32 v57, 0x3d372713, v34
	ds_write2_b64 v56, v[200:201], v[58:59] offset1:2
	v_cvt_pk_bf16_f32 v32, v32, v33
	v_mul_f32_e32 v33, 0x3fcc422a, v34
	v_fma_f32 v57, v34, v57, 1.0
	v_mul_f32_e32 v58, 0x3d372713, v35
	v_mul_f32_e32 v33, v33, v57
	v_mul_f32_e32 v57, 0x3fcc422a, v35
	v_fma_f32 v58, v35, v58, 1.0
	v_mul_f32_e32 v33, 0xbfb8aa3b, v33
	v_mul_f32_e32 v57, v57, v58
	v_exp_f32_e32 v33, v33
	v_mul_f32_e32 v57, 0xbfb8aa3b, v57
	v_exp_f32_e32 v57, v57
	v_mfma_f32_32x32x16_bf16 v[16:31], v[128:131], v[120:123], v[16:31]
	v_add_f32_e32 v33, 1.0, v33
	v_rcp_f32_e32 v58, v33
	v_add_f32_e32 v33, 1.0, v57
	v_mul_f32_e32 v57, 0x3d372713, v36
	v_rcp_f32_e32 v59, v33
	v_mul_f32_e32 v33, 0x3fcc422a, v36
	v_fma_f32 v57, v36, v57, 1.0
	v_mul_f32_e32 v60, 0x3d372713, v37
	v_mul_f32_e32 v33, v33, v57
	v_mul_f32_e32 v57, 0x3fcc422a, v37
	v_fma_f32 v60, v37, v60, 1.0
	v_mul_f32_e32 v33, 0xbfb8aa3b, v33
	v_mul_f32_e32 v57, v57, v60
	v_exp_f32_e32 v33, v33
	v_mul_f32_e32 v57, 0xbfb8aa3b, v57
	v_exp_f32_e32 v57, v57
	s_waitcnt vmcnt(5)
	v_mfma_f32_32x32x16_bf16 v[16:31], v[184:187], v[116:119], v[16:31]
	v_mul_f32_e64 v34, v34, v58
	v_mul_f32_e64 v35, v35, v59
	v_add_f32_e32 v33, 1.0, v33
	v_mul_f32_e32 v59, 0x3d372713, v38
	v_rcp_f32_e32 v58, v33
	v_add_f32_e32 v33, 1.0, v57
	v_mul_f32_e32 v57, 0x3fcc422a, v38
	v_fma_f32 v59, v38, v59, 1.0
	v_mul_f32_e32 v60, 0x3d372713, v39
	v_mul_f32_e32 v57, v57, v59
	v_mul_f32_e32 v59, 0x3fcc422a, v39
	v_fma_f32 v60, v39, v60, 1.0
	v_mul_f32_e32 v57, 0xbfb8aa3b, v57
	v_mul_f32_e32 v59, v59, v60
	v_exp_f32_e32 v57, v57
	v_mul_f32_e32 v59, 0xbfb8aa3b, v59
	v_exp_f32_e32 v61, v59
	s_waitcnt vmcnt(3)
	v_mfma_f32_32x32x16_bf16 v[16:31], v[192:195], v[112:115], v[16:31]
	v_rcp_f32_e32 v59, v33
	v_add_f32_e32 v33, 1.0, v57
	v_rcp_f32_e32 v60, v33
	v_add_f32_e32 v33, 1.0, v61
	v_rcp_f32_e32 v61, v33
	v_cvt_pk_bf16_f32 v33, v34, v35
	v_pk_mul_f32 v[34:35], v[36:37], v[58:59]
	v_mfma_f32_32x32x16_bf16 v[16:31], v[144:147], v[108:111], v[16:31]
	v_mul_f32_e64 v36, v38, v60
	v_mul_f32_e64 v37, v39, v61
	v_mul_f32_e32 v38, 0x3d372713, v40
	v_cvt_pk_bf16_f32 v34, v34, v35
	v_mul_f32_e32 v35, 0x3fcc422a, v40
	v_fma_f32 v38, v40, v38, 1.0
	v_mul_f32_e32 v35, v35, v38
	v_mul_f32_e32 v35, 0xbfb8aa3b, v35
	v_mul_f32_e32 v39, 0x3d372713, v41
	v_exp_f32_e32 v38, v35
	v_mul_f32_e32 v35, 0x3fcc422a, v41
	v_fma_f32 v39, v41, v39, 1.0
	v_mul_f32_e32 v35, v35, v39
	v_mul_f32_e32 v35, 0xbfb8aa3b, v35
	v_exp_f32_e32 v39, v35
	v_mfma_f32_32x32x16_bf16 v[16:31], v[204:207], v[164:167], v[16:31]
	v_cvt_pk_bf16_f32 v35, v36, v37
	v_add_f32_e32 v36, 1.0, v38
	v_add_f32_e32 v37, 1.0, v39
	v_mul_f32_e32 v39, 0x3d372713, v42
	v_mul_f32_e32 v38, 0x3fcc422a, v42
	v_fma_f32 v39, v42, v39, 1.0
	v_mul_f32_e32 v57, 0x3d372713, v43
	v_mul_f32_e32 v38, v38, v39
	v_mul_f32_e32 v39, 0x3fcc422a, v43
	v_fma_f32 v57, v43, v57, 1.0
	v_mul_f32_e32 v39, v39, v57
	v_mul_f32_e32 v38, 0xbfb8aa3b, v38
	v_mul_f32_e32 v39, 0xbfb8aa3b, v39
	s_waitcnt vmcnt(2)
	v_mfma_f32_32x32x16_bf16 v[16:31], v[224:227], v[156:159], v[16:31]
	v_exp_f32_e32 v38, v38
	v_exp_f32_e32 v39, v39
	v_rcp_f32_e32 v36, v36
	v_rcp_f32_e32 v37, v37
	v_add_f32_e32 v38, 1.0, v38
	v_add_f32_e32 v39, 1.0, v39
	v_rcp_f32_e32 v38, v38
	v_mfma_f32_32x32x16_bf16 v[0:15], v[88:91], v[76:79], v[0:15]
	v_rcp_f32_e32 v39, v39
	ds_write2_b64 v230, v[32:33], v[34:35] offset0:128 offset1:130
	v_pk_mul_f32 v[32:33], v[40:41], v[36:37]
	v_mul_f32_e32 v36, 0x3d372713, v45
	v_pk_mul_f32 v[34:35], v[42:43], v[38:39]
	v_cvt_pk_bf16_f32 v32, v32, v33
	v_cvt_pk_bf16_f32 v33, v34, v35
	s_waitcnt vmcnt(1)
	v_mfma_f32_32x32x16_bf16 v[16:31], v[220:223], v[152:155], v[16:31]
	v_mul_f32_e32 v35, 0x3d372713, v44
	v_mul_f32_e32 v34, 0x3fcc422a, v44
	v_fma_f32 v35, v44, v35, 1.0
	v_mul_f32_e32 v34, v34, v35
	v_mul_f32_e32 v35, 0x3fcc422a, v45
	v_fma_f32 v36, v45, v36, 1.0
	v_mul_f32_e32 v35, v35, v36
	v_mfma_f32_32x32x16_bf16 v[0:15], v[92:95], v[80:83], v[0:15]
	v_mul_f32_e32 v34, 0xbfb8aa3b, v34
	v_mul_f32_e32 v35, 0xbfb8aa3b, v35
	v_exp_f32_e32 v34, v34
	v_exp_f32_e32 v35, v35
	v_mul_f32_e32 v37, 0x3d372713, v46
	v_mul_f32_e32 v36, 0x3fcc422a, v46
	v_add_f32_e32 v34, 1.0, v34
	s_waitcnt vmcnt(0)
	v_mfma_f32_32x32x16_bf16 v[16:31], v[52:55], v[168:171], v[16:31]
	v_add_f32_e32 v35, 1.0, v35
	v_rcp_f32_e32 v34, v34
	v_fma_f32 v37, v46, v37, 1.0
	v_mul_f32_e32 v38, 0x3d372713, v47
	v_rcp_f32_e32 v35, v35
	v_mul_f32_e32 v36, v36, v37
	v_mul_f32_e32 v37, 0x3fcc422a, v47
	v_mfma_f32_32x32x16_bf16 v[0:15], v[136:139], v[104:107], v[0:15]
	v_fma_f32 v38, v47, v38, 1.0
	v_mul_f32_e32 v37, v37, v38
	v_mul_f32_e32 v36, 0xbfb8aa3b, v36
	v_mul_f32_e32 v37, 0xbfb8aa3b, v37
	v_exp_f32_e32 v36, v36
	v_exp_f32_e32 v37, v37
	v_pk_mul_f32 v[34:35], v[44:45], v[34:35]
	v_mfma_f32_32x32x16_bf16 v[0:15], v[196:199], v[132:135], v[0:15]
	v_mul_f32_e32 v38, 0x3d372713, v16
	v_cvt_pk_bf16_f32 v34, v34, v35
	v_mul_f32_e32 v35, 0x3fcc422a, v16
	v_fma_f32 v38, v16, v38, 1.0
	v_mul_f32_e32 v39, 0x3d372713, v17
	v_mul_f32_e32 v35, v35, v38
	v_mul_f32_e32 v38, 0x3fcc422a, v17
	v_fma_f32 v39, v17, v39, 1.0
	v_mul_f32_e32 v35, 0xbfb8aa3b, v35
	v_mul_f32_e32 v38, v38, v39
	v_add_f32_e32 v36, 1.0, v36
	v_add_f32_e32 v37, 1.0, v37
	v_exp_f32_e32 v35, v35
	v_mul_f32_e32 v38, 0xbfb8aa3b, v38
	v_rcp_f32_e32 v36, v36
	v_rcp_f32_e32 v37, v37
	v_exp_f32_e32 v39, v38
	v_mfma_f32_32x32x16_bf16 v[0:15], v[188:191], v[180:183], v[0:15]
	v_add_f32_e32 v35, 1.0, v35
	v_mul_f32_e64 v36, v46, v36
	v_mul_f32_e64 v37, v47, v37
	v_rcp_f32_e32 v38, v35
	v_add_f32_e32 v35, 1.0, v39
	v_rcp_f32_e32 v39, v35
	v_cvt_pk_bf16_f32 v35, v36, v37
	v_add_u32_e32 v36, 0x800, v230
	ds_write2_b64 v36, v[32:33], v[34:35] offset0:128 offset1:130
	v_mul_f32_e32 v33, 0x3d372713, v18
	v_mul_f32_e32 v32, 0x3fcc422a, v18
	v_fma_f32 v33, v18, v33, 1.0
	v_mul_f32_e32 v34, 0x3d372713, v19
	v_mul_f32_e32 v32, v32, v33
	v_mul_f32_e32 v33, 0x3fcc422a, v19
	v_fma_f32 v34, v19, v34, 1.0
	v_mul_f32_e32 v35, 0x3d372713, v20
	v_mul_f32_e32 v33, v33, v34
	v_mul_f32_e32 v34, 0x3fcc422a, v20
	v_fma_f32 v35, v20, v35, 1.0
	v_mul_f32_e32 v36, 0x3d372713, v21
	v_mul_f32_e32 v34, v34, v35
	v_mul_f32_e32 v35, 0x3fcc422a, v21
	v_fma_f32 v36, v21, v36, 1.0
	v_mfma_f32_32x32x16_bf16 v[0:15], v[128:131], v[176:179], v[0:15]
	v_mul_f32_e32 v32, 0xbfb8aa3b, v32
	v_mul_f32_e32 v33, 0xbfb8aa3b, v33
	v_mul_f32_e32 v35, v35, v36
	v_exp_f32_e32 v32, v32
	v_exp_f32_e32 v33, v33
	v_mul_f32_e32 v34, 0xbfb8aa3b, v34
	v_mul_f32_e32 v35, 0xbfb8aa3b, v35
	v_exp_f32_e32 v34, v34
	v_exp_f32_e32 v35, v35
	v_add_f32_e32 v32, 1.0, v32
	v_add_f32_e32 v33, 1.0, v33
	v_rcp_f32_e32 v32, v32
	v_rcp_f32_e32 v33, v33
	v_add_f32_e32 v34, 1.0, v34
	v_add_f32_e32 v35, 1.0, v35
	v_rcp_f32_e32 v34, v34
	v_rcp_f32_e32 v35, v35
	v_mfma_f32_32x32x16_bf16 v[0:15], v[184:187], v[172:175], v[0:15]
	v_mul_f32_e64 v16, v16, v38
	v_mul_f32_e64 v17, v17, v39
	v_mul_f32_e64 v18, v18, v32
	v_mul_f32_e64 v19, v19, v33
	v_cvt_pk_bf16_f32 v16, v16, v17
	v_cvt_pk_bf16_f32 v17, v18, v19
	v_pk_mul_f32 v[18:19], v[20:21], v[34:35]
	v_mul_f32_e32 v21, 0x3d372713, v22
	v_mul_f32_e32 v20, 0x3fcc422a, v22
	v_fma_f32 v21, v22, v21, 1.0
	v_mul_f32_e32 v32, 0x3d372713, v23
	v_mul_f32_e32 v20, v20, v21
	v_mul_f32_e32 v21, 0x3fcc422a, v23
	v_fma_f32 v32, v23, v32, 1.0
	v_mul_f32_e32 v20, 0xbfb8aa3b, v20
	v_mul_f32_e32 v21, v21, v32
	v_exp_f32_e32 v20, v20
	v_mul_f32_e32 v21, 0xbfb8aa3b, v21
	v_mfma_f32_32x32x16_bf16 v[0:15], v[192:195], v[160:163], v[0:15]
	v_exp_f32_e32 v21, v21
	v_cvt_pk_bf16_f32 v18, v18, v19
	v_add_f32_e32 v19, 1.0, v20
	v_rcp_f32_e32 v20, v19
	v_add_f32_e32 v19, 1.0, v21
	v_mul_f32_e32 v32, 0x3d372713, v24
	v_rcp_f32_e32 v21, v19
	v_mul_f32_e32 v19, 0x3fcc422a, v24
	v_fma_f32 v32, v24, v32, 1.0
	v_mul_f32_e32 v33, 0x3d372713, v25
	v_mul_f32_e32 v19, v19, v32
	v_mul_f32_e32 v32, 0x3fcc422a, v25
	v_fma_f32 v33, v25, v33, 1.0
	v_mul_f32_e32 v19, 0xbfb8aa3b, v19
	v_mul_f32_e32 v32, v32, v33
	v_mfma_f32_32x32x16_bf16 v[0:15], v[144:147], v[148:151], v[0:15]
	v_exp_f32_e32 v19, v19
	v_mul_f32_e32 v32, 0xbfb8aa3b, v32
	v_exp_f32_e32 v32, v32
	v_pk_mul_f32 v[20:21], v[22:23], v[20:21]
	v_add_f32_e32 v19, 1.0, v19
	v_rcp_f32_e32 v22, v19
	v_add_f32_e32 v19, 1.0, v32
	v_rcp_f32_e32 v23, v19
	v_cvt_pk_bf16_f32 v19, v20, v21
	v_add_u32_e32 v32, 0x1000, v230
	ds_write2_b64 v32, v[16:17], v[18:19] offset1:2
	v_mul_f32_e32 v19, 0x3d372713, v26
	v_mfma_f32_32x32x16_bf16 v[0:15], v[204:207], v[208:211], v[0:15]
	v_mul_f32_e32 v18, 0x3fcc422a, v26
	v_fma_f32 v19, v26, v19, 1.0
	v_mul_f32_e32 v20, 0x3d372713, v27
	v_mul_f32_e32 v18, v18, v19
	v_mul_f32_e32 v19, 0x3fcc422a, v27
	v_fma_f32 v20, v27, v20, 1.0
	v_mul_f32_e32 v18, 0xbfb8aa3b, v18
	v_mul_f32_e32 v19, v19, v20
	v_exp_f32_e32 v18, v18
	v_mul_f32_e32 v19, 0xbfb8aa3b, v19
	v_exp_f32_e32 v19, v19
	v_pk_mul_f32 v[16:17], v[24:25], v[22:23]
	v_mfma_f32_32x32x16_bf16 v[0:15], v[224:227], v[212:215], v[0:15]
	v_cvt_pk_bf16_f32 v16, v16, v17
	v_add_f32_e32 v17, 1.0, v18
	v_rcp_f32_e32 v18, v17
	v_add_f32_e32 v17, 1.0, v19
	v_mul_f32_e32 v20, 0x3d372713, v28
	v_rcp_f32_e32 v19, v17
	v_mul_f32_e32 v17, 0x3fcc422a, v28
	v_fma_f32 v20, v28, v20, 1.0
	v_mul_f32_e32 v21, 0x3d372713, v29
	v_mul_f32_e32 v17, v17, v20
	v_mul_f32_e32 v20, 0x3fcc422a, v29
	v_fma_f32 v21, v29, v21, 1.0
	v_mul_f32_e32 v17, 0xbfb8aa3b, v17
	v_mul_f32_e32 v20, v20, v21
	v_exp_f32_e32 v17, v17
	v_mul_f32_e32 v20, 0xbfb8aa3b, v20
	v_exp_f32_e32 v21, v20
	v_mfma_f32_32x32x16_bf16 v[0:15], v[220:223], v[216:219], v[0:15]
	v_add_f32_e32 v17, 1.0, v17
	v_mul_f32_e32 v22, 0x3d372713, v30
	v_rcp_f32_e32 v20, v17
	v_add_f32_e32 v17, 1.0, v21
	v_mul_f32_e32 v21, 0x3fcc422a, v30
	v_fma_f32 v22, v30, v22, 1.0
	v_mul_f32_e32 v21, v21, v22
	v_mul_f32_e32 v21, 0xbfb8aa3b, v21
	v_mul_f32_e32 v23, 0x3d372713, v31
	v_exp_f32_e32 v22, v21
	v_mul_f32_e32 v21, 0x3fcc422a, v31
	v_fma_f32 v23, v31, v23, 1.0
	v_mul_f32_e32 v21, v21, v23
	v_mul_f32_e32 v21, 0xbfb8aa3b, v21
	v_exp_f32_e32 v23, v21
	v_mfma_f32_32x32x16_bf16 v[0:15], v[52:55], v[48:51], v[0:15]
	v_rcp_f32_e32 v21, v17
	v_add_f32_e32 v17, 1.0, v22
	v_rcp_f32_e32 v22, v17
	v_add_f32_e32 v17, 1.0, v23
	v_rcp_f32_e32 v23, v17
	v_pk_mul_f32 v[18:19], v[26:27], v[18:19]
	s_nop 0
	v_cvt_pk_bf16_f32 v17, v18, v19
	v_pk_mul_f32 v[18:19], v[28:29], v[20:21]
	v_pk_mul_f32 v[20:21], v[30:31], v[22:23]
	s_nop 1
	v_mul_f32_e32 v22, 0x3d372713, v0
	v_cvt_pk_bf16_f32 v18, v18, v19
	v_cvt_pk_bf16_f32 v19, v20, v21
	v_mul_f32_e32 v21, 0x3fcc422a, v0
	v_fma_f32 v22, v0, v22, 1.0
	v_mul_f32_e32 v23, 0x3d372713, v1
	v_mul_f32_e32 v21, v21, v22
	v_mul_f32_e32 v22, 0x3fcc422a, v1
	v_fma_f32 v23, v1, v23, 1.0
	v_mul_f32_e32 v22, v22, v23
	v_add_u32_e32 v20, 0x1000, v56
	v_mul_f32_e32 v21, 0xbfb8aa3b, v21
	v_mul_f32_e32 v22, 0xbfb8aa3b, v22
	v_exp_f32_e32 v21, v21
	v_exp_f32_e32 v22, v22
	ds_write2_b64 v20, v[16:17], v[18:19] offset1:2
	v_mul_f32_e32 v19, 0x3d372713, v2
	v_mul_f32_e32 v18, 0x3fcc422a, v2
	v_fma_f32 v19, v2, v19, 1.0
	v_mul_f32_e32 v20, 0x3d372713, v3
	v_mul_f32_e32 v18, v18, v19
	v_mul_f32_e32 v19, 0x3fcc422a, v3
	v_fma_f32 v20, v3, v20, 1.0
	v_mul_f32_e32 v19, v19, v20
	v_add_f32_e32 v16, 1.0, v21
	v_add_f32_e32 v17, 1.0, v22
	v_mul_f32_e32 v19, 0xbfb8aa3b, v19
	v_rcp_f32_e32 v16, v16
	v_rcp_f32_e32 v17, v17
	v_mul_f32_e32 v18, 0xbfb8aa3b, v18
	v_exp_f32_e32 v19, v19
	v_exp_f32_e32 v18, v18
	v_pk_mul_f32 v[0:1], v[0:1], v[16:17]
	v_mul_f32_e32 v20, 0x3d372713, v5
	v_add_f32_e32 v17, 1.0, v19
	v_mul_f32_e32 v19, 0x3d372713, v4
	v_add_f32_e32 v16, 1.0, v18
	v_mul_f32_e32 v18, 0x3fcc422a, v4
	v_fma_f32 v19, v4, v19, 1.0
	v_mul_f32_e32 v18, v18, v19
	v_mul_f32_e32 v19, 0x3fcc422a, v5
	v_fma_f32 v20, v5, v20, 1.0
	v_mul_f32_e32 v19, v19, v20
	v_mul_f32_e32 v18, 0xbfb8aa3b, v18
	v_mul_f32_e32 v19, 0xbfb8aa3b, v19
	v_exp_f32_e32 v18, v18
	v_exp_f32_e32 v19, v19
	v_rcp_f32_e32 v16, v16
	v_rcp_f32_e32 v17, v17
	v_add_f32_e32 v18, 1.0, v18
	v_add_f32_e32 v19, 1.0, v19
	v_rcp_f32_e32 v18, v18
	v_rcp_f32_e32 v19, v19
	v_pk_mul_f32 v[2:3], v[2:3], v[16:17]
	v_cvt_pk_bf16_f32 v0, v0, v1
	v_cvt_pk_bf16_f32 v1, v2, v3
	v_pk_mul_f32 v[2:3], v[4:5], v[18:19]
	v_mul_f32_e32 v5, 0x3d372713, v6
	v_mul_f32_e32 v4, 0x3fcc422a, v6
	v_fma_f32 v5, v6, v5, 1.0
	v_mul_f32_e32 v16, 0x3d372713, v7
	v_mul_f32_e32 v4, v4, v5
	v_mul_f32_e32 v5, 0x3fcc422a, v7
	v_fma_f32 v16, v7, v16, 1.0
	v_mul_f32_e32 v4, 0xbfb8aa3b, v4
	v_mul_f32_e32 v5, v5, v16
	v_exp_f32_e32 v4, v4
	v_mul_f32_e32 v5, 0xbfb8aa3b, v5
	v_exp_f32_e32 v5, v5
	v_cvt_pk_bf16_f32 v2, v2, v3
	v_add_f32_e32 v3, 1.0, v4
	v_mul_f32_e32 v16, 0x3d372713, v8
	v_rcp_f32_e32 v4, v3
	v_add_f32_e32 v3, 1.0, v5
	v_mul_f32_e32 v5, 0x3fcc422a, v8
	v_fma_f32 v16, v8, v16, 1.0
	v_mul_f32_e32 v5, v5, v16
	v_mul_f32_e32 v5, 0xbfb8aa3b, v5
	v_mul_f32_e32 v17, 0x3d372713, v9
	v_exp_f32_e32 v16, v5
	v_mul_f32_e32 v5, 0x3fcc422a, v9
	v_fma_f32 v17, v9, v17, 1.0
	v_mul_f32_e32 v5, v5, v17
	v_mul_f32_e32 v5, 0xbfb8aa3b, v5
	v_exp_f32_e32 v17, v5
	v_rcp_f32_e32 v5, v3
	v_add_f32_e32 v3, 1.0, v16
	v_rcp_f32_e32 v16, v3
	v_add_f32_e32 v3, 1.0, v17
	v_pk_mul_f32 v[4:5], v[6:7], v[4:5]
	v_rcp_f32_e32 v17, v3
	v_cvt_pk_bf16_f32 v3, v4, v5
	ds_write2_b64 v32, v[0:1], v[2:3] offset0:128 offset1:130
	v_mul_f32_e32 v3, 0x3d372713, v10
	v_mul_f32_e32 v2, 0x3fcc422a, v10
	v_fma_f32 v3, v10, v3, 1.0
	v_mul_f32_e32 v4, 0x3d372713, v11
	v_mul_f32_e32 v2, v2, v3
	v_mul_f32_e32 v3, 0x3fcc422a, v11
	v_fma_f32 v4, v11, v4, 1.0
	v_mul_f32_e32 v2, 0xbfb8aa3b, v2
	v_mul_f32_e32 v3, v3, v4
	v_exp_f32_e32 v2, v2
	v_mul_f32_e32 v3, 0xbfb8aa3b, v3
	v_exp_f32_e32 v3, v3
	v_pk_mul_f32 v[0:1], v[8:9], v[16:17]
	v_mul_f32_e32 v4, 0x3d372713, v12
	v_cvt_pk_bf16_f32 v0, v0, v1
	v_add_f32_e32 v1, 1.0, v2
	v_rcp_f32_e32 v2, v1
	v_add_f32_e32 v1, 1.0, v3
	v_rcp_f32_e32 v3, v1
	v_mul_f32_e32 v1, 0x3fcc422a, v12
	v_fma_f32 v4, v12, v4, 1.0
	v_mul_f32_e32 v5, 0x3d372713, v13
	v_mul_f32_e32 v1, v1, v4
	v_mul_f32_e32 v4, 0x3fcc422a, v13
	v_fma_f32 v5, v13, v5, 1.0
	v_mul_f32_e32 v1, 0xbfb8aa3b, v1
	v_mul_f32_e32 v4, v4, v5
	v_exp_f32_e32 v1, v1
	v_mul_f32_e32 v4, 0xbfb8aa3b, v4
	v_exp_f32_e32 v5, v4
	v_mul_f32_e32 v6, 0x3d372713, v14
	v_add_f32_e32 v1, 1.0, v1
	v_rcp_f32_e32 v4, v1
	v_add_f32_e32 v1, 1.0, v5
	v_mul_f32_e32 v5, 0x3fcc422a, v14
	v_fma_f32 v6, v14, v6, 1.0
	v_mul_f32_e32 v5, v5, v6
	v_mul_f32_e32 v5, 0xbfb8aa3b, v5
	v_mul_f32_e32 v7, 0x3d372713, v15
	v_exp_f32_e32 v6, v5
	v_mul_f32_e32 v5, 0x3fcc422a, v15
	v_fma_f32 v7, v15, v7, 1.0
	v_mul_f32_e32 v5, v5, v7
	v_mul_f32_e32 v5, 0xbfb8aa3b, v5
	v_exp_f32_e32 v7, v5
	v_rcp_f32_e32 v5, v1
	v_add_f32_e32 v1, 1.0, v6
	v_rcp_f32_e32 v6, v1
	v_add_f32_e32 v1, 1.0, v7
	v_rcp_f32_e32 v7, v1
	v_pk_mul_f32 v[2:3], v[10:11], v[2:3]
	s_nop 0
	v_cvt_pk_bf16_f32 v1, v2, v3
	v_pk_mul_f32 v[2:3], v[12:13], v[4:5]
	v_pk_mul_f32 v[4:5], v[14:15], v[6:7]
	v_cvt_pk_bf16_f32 v2, v2, v3
	v_cvt_pk_bf16_f32 v3, v4, v5
	v_add_u32_e32 v4, 0x1800, v230
	ds_write2_b64 v4, v[0:1], v[2:3] offset0:128 offset1:130
	v_lshlrev_b32_e32 v0, 4, v235
	v_and_b32_e32 v232, 0x3e0, v0
	s_waitcnt lgkmcnt(0)
	v_add3_u32 v14, s5, v234, v232
	ds_read_b128 v[0:3], v14
	v_mov_b32_e32 v235, v233
	v_lshl_add_u64 v[4:5], s[0:1], 0, v[232:233]
	v_lshl_add_u64 v[8:9], s[6:7], 0, v[234:235]
	v_lshlrev_b64 v[4:5], 11, v[4:5]
	v_lshl_add_u64 v[10:11], v[8:9], 0, v[4:5]
	ds_read_b128 v[4:7], v14 offset:1024
	s_waitcnt lgkmcnt(1)
	global_store_dwordx4 v[10:11], v[0:3], off
	v_or_b32_e32 v10, 0x400, v232
	v_mov_b32_e32 v11, v233
	v_lshl_add_u64 v[0:1], s[0:1], 0, v[10:11]
	v_lshlrev_b64 v[0:1], 11, v[0:1]
	v_lshl_add_u64 v[0:1], v[8:9], 0, v[0:1]
	s_waitcnt lgkmcnt(0)
	global_store_dwordx4 v[0:1], v[4:7], off
	ds_read_b128 v[0:3], v14 offset:2048
	s_mov_b32 s5, s1
	v_lshl_add_u64 v[4:5], s[4:5], 0, v[232:233]
	v_lshlrev_b64 v[4:5], 11, v[4:5]
	v_lshl_add_u64 v[12:13], v[8:9], 0, v[4:5]
	ds_read_b128 v[4:7], v14 offset:3072
	s_waitcnt lgkmcnt(1)
	global_store_dwordx4 v[12:13], v[0:3], off
	s_nop 1
	v_lshl_add_u64 v[0:1], s[4:5], 0, v[10:11]
	v_lshlrev_b64 v[0:1], 11, v[0:1]
	v_lshl_add_u64 v[0:1], v[8:9], 0, v[0:1]
	s_waitcnt lgkmcnt(0)
	global_store_dwordx4 v[0:1], v[4:7], off
	ds_read_b128 v[0:3], v14 offset:4096
	s_or_b32 s4, s0, 2
	v_lshl_add_u64 v[4:5], s[4:5], 0, v[232:233]
	v_lshlrev_b64 v[4:5], 11, v[4:5]
	v_lshl_add_u64 v[12:13], v[8:9], 0, v[4:5]
	ds_read_b128 v[4:7], v14 offset:5120
	s_waitcnt lgkmcnt(1)
	global_store_dwordx4 v[12:13], v[0:3], off
	s_or_b32 s0, s0, 3
	s_cmpk_gt_i32 s22, 0xff
	v_lshl_add_u64 v[0:1], s[4:5], 0, v[10:11]
	v_lshlrev_b64 v[0:1], 11, v[0:1]
	v_lshl_add_u64 v[0:1], v[8:9], 0, v[0:1]
	s_waitcnt lgkmcnt(0)
	global_store_dwordx4 v[0:1], v[4:7], off
	ds_read_b128 v[0:3], v14 offset:6144
	s_nop 0
	v_lshl_add_u64 v[4:5], s[0:1], 0, v[232:233]
	v_lshlrev_b64 v[4:5], 11, v[4:5]
	v_lshl_add_u64 v[12:13], v[8:9], 0, v[4:5]
	ds_read_b128 v[4:7], v14 offset:7168
	s_waitcnt lgkmcnt(1)
	global_store_dwordx4 v[12:13], v[0:3], off
	s_nop 1
	v_lshl_add_u64 v[0:1], s[0:1], 0, v[10:11]
	v_lshlrev_b64 v[0:1], 11, v[0:1]
	v_lshl_add_u64 v[0:1], v[8:9], 0, v[0:1]
	s_waitcnt lgkmcnt(0)
	global_store_dwordx4 v[0:1], v[4:7], off
	s_barrier
	s_cbranch_scc0 .LBB0_435
